# ex_chunk K loop unrolled with 32 loads in flight; final RMSNorm weight loads hoisted out of the row loop; GLU loop 6 weight sets paired loads
# speedup vs baseline: 1.0118x; 1.0043x over previous
.LBB0_11:
	v_readlane_b32 s4, v250, 6
	v_readlane_b32 s8, v252, 51
	v_readlane_b32 s6, v250, 8
	v_readlane_b32 s9, v252, 52
	v_readlane_b32 s10, v251, 62
	v_readlane_b32 s12, v252, 49
	v_readlane_b32 s14, v252, 53
	v_writelane_b32 v253, s52, 50
	s_mov_b64 s[22:23], -1
	s_mov_b64 s[2:3], 0
	s_cmp_lt_i32 s6, 21
	s_mov_b64 s[0:1], 0
	v_readlane_b32 s11, v251, 63
	v_readlane_b32 s13, v252, 50
	v_readlane_b32 s15, v252, 54
	s_mov_b32 s9, 0xf800000
	v_readlane_b32 s5, v250, 7
	v_readlane_b32 s7, v250, 9
	s_cbranch_scc1 .LBB0_18
	v_readlane_b32 s4, v250, 6
	v_readlane_b32 s6, v250, 8
	s_cmp_eq_u32 s6, 21
	s_mov_b64 s[0:1], -1
	v_readlane_b32 s5, v250, 7
	v_readlane_b32 s7, v250, 9
	s_cbranch_scc0 .LBB0_17
	v_mov_b32_e32 v6, v0
	v_readlane_b32 s0, v252, 41
	v_ashrrev_i32_e32 v8, 6, v6
	v_readlane_b32 s1, v252, 42
	s_waitcnt lgkmcnt(0)
	v_add_u32_e32 v1, s0, v8
	v_cmp_gt_i32_e32 vcc, s69, v1
	s_and_saveexec_b64 s[22:23], vcc
	v_readlane_b32 s4, v250, 6
	v_readlane_b32 s5, v250, 7
	v_readlane_b32 s6, v250, 8
	v_readlane_b32 s7, v250, 9
	s_cbranch_execz .LBB0_16
	s_mov_b64 s[0:1], s[50:51]
	v_readlane_b32 s36, v252, 0
	v_readlane_b32 s50, v252, 14
	v_readlane_b32 s51, v252, 15
	s_mov_b64 s[50:51], s[0:1]
	v_readlane_b32 s0, v252, 41
	v_ashrrev_i32_e32 v9, 31, v8
	v_readlane_b32 s1, v252, 42
	v_and_b32_e32 v14, 63, v6
	v_lshlrev_b32_e32 v138, 4, v14
	v_lshl_add_u64 v[12:13], s[0:1], 0, v[8:9]
	v_lshlrev_b64 v[10:11], 12, v[12:13]
	v_readlane_b32 s0, v252, 16
	v_lshlrev_b64 v[8:9], 6, v[12:13]
	v_or_b32_e32 v10, v10, v138
	v_readlane_b32 s1, v252, 17
	v_lshlrev_b64 v[12:13], 11, v[12:13]
	v_readlane_b32 s48, v252, 12
	v_readlane_b32 s49, v252, 13
	v_lshl_add_u64 v[10:11], s[0:1], 0, v[10:11]
	v_lshl_or_b32 v12, v14, 3, v12
	s_mov_b64 s[0:1], 0xfd00400
	v_lshl_add_u64 v[6:7], s[48:49], 0, v[138:139]
	v_lshl_add_u64 v[12:13], v[12:13], 0, s[0:1]
	s_mov_b64 s[24:25], 0
	v_readlane_b32 s37, v252, 1
	v_readlane_b32 s38, v252, 2
	v_readlane_b32 s39, v252, 3
	v_readlane_b32 s40, v252, 4
	v_readlane_b32 s41, v252, 5
	v_readlane_b32 s42, v252, 6
	v_readlane_b32 s43, v252, 7
	v_readlane_b32 s44, v252, 8
	v_readlane_b32 s45, v252, 9
	v_readlane_b32 s46, v252, 10
	v_readlane_b32 s47, v252, 11
	global_load_dwordx4 v[30:33], v[6:7], off
	global_load_dwordx4 v[44:47], v[6:7], off offset:1024
	global_load_dwordx4 v[48:51], v[6:7], off offset:2048
	global_load_dwordx4 v[52:55], v[6:7], off offset:3072
.LBB0_15:
	v_lshl_add_u64 v[14:15], s[4:5], 0, v[8:9]
	s_mov_b64 s[0:1], 0x12900000
	v_add_co_u32_e32 v22, vcc, 0x12900000, v14
	v_lshl_add_u64 v[34:35], s[4:5], 0, v[12:13]
	v_lshl_add_u64 v[26:27], v[14:15], 0, s[0:1]
	v_addc_co_u32_e32 v23, vcc, 0, v15, vcc
	global_load_dwordx4 v[14:17], v[26:27], off offset:32
	global_load_dwordx4 v[18:21], v[26:27], off offset:16
	s_nop 0
	global_load_dwordx4 v[22:25], v[22:23], off
	s_nop 0
	global_load_dwordx4 v[26:29], v[26:27], off offset:48
	s_nop 0
	global_load_dwordx2 v[36:37], v[34:35], off offset:-1024
	global_load_dwordx2 v[38:39], v[34:35], off offset:-512
	global_load_dwordx2 v[40:41], v[34:35], off
	s_nop 0
	global_load_dwordx2 v[34:35], v[34:35], off offset:512
	v_add_u32_e32 v1, s8, v1
	v_lshl_add_u64 v[8:9], v[8:9], 0, s[10:11]
	v_lshl_add_u64 v[12:13], v[12:13], 0, s[14:15]
	s_waitcnt vmcnt(0)
	v_add_f32_e32 v22, 0, v22
	v_add_f32_e32 v22, v22, v23
	v_add_f32_e32 v22, v22, v24
	v_add_f32_e32 v22, v22, v25
	v_add_f32_e32 v18, v22, v18
	v_add_f32_e32 v18, v18, v19
	v_add_f32_e32 v18, v18, v20
	v_add_f32_e32 v18, v18, v21
	v_add_f32_e32 v14, v18, v14
	v_add_f32_e32 v14, v14, v15
	v_add_f32_e32 v14, v14, v16
	v_add_f32_e32 v14, v14, v17
	s_waitcnt vmcnt(5)
	v_add_f32_e32 v14, v14, v26
	v_add_f32_e32 v14, v14, v27
	v_add_f32_e32 v14, v14, v28
	v_add_f32_e32 v14, v14, v29
	v_fmamk_f32 v14, v14, 0x3a800000, v223
	v_mul_f32_e32 v15, 0x4f800000, v14
	v_cmp_gt_f32_e32 vcc, s9, v14
	s_waitcnt vmcnt(4)
	v_lshlrev_b32_e32 v42, 16, v36
	v_and_b32_e32 v43, 0xffff0000, v36
	v_cndmask_b32_e32 v14, v14, v15, vcc
	v_sqrt_f32_e32 v15, v14
	v_lshlrev_b32_e32 v36, 16, v37
	v_and_b32_e32 v37, 0xffff0000, v37
	s_waitcnt vmcnt(2)
	v_lshlrev_b32_e32 v20, 16, v38
	v_add_u32_e32 v16, -1, v15
	v_add_u32_e32 v17, 1, v15
	v_fma_f32 v18, -v16, v15, v14
	v_fma_f32 v19, -v17, v15, v14
	v_cmp_ge_f32_e64 s[0:1], 0, v18
	v_and_b32_e32 v21, 0xffff0000, v38
	v_lshlrev_b32_e32 v22, 16, v39
	v_cndmask_b32_e64 v15, v15, v16, s[0:1]
	v_cmp_lt_f32_e64 s[0:1], 0, v19
	v_and_b32_e32 v23, 0xffff0000, v39
	s_nop 0
	v_cndmask_b32_e64 v15, v15, v17, s[0:1]
	v_mul_f32_e32 v16, 0x37800000, v15
	v_cndmask_b32_e32 v15, v15, v16, vcc
	v_cmp_class_f32_e32 vcc, v14, v224
	s_nop 1
	v_cndmask_b32_e32 v14, v15, v14, vcc
	v_div_scale_f32 v15, s[0:1], v14, v14, 1.0
	v_rcp_f32_e32 v17, v15
	v_div_scale_f32 v16, vcc, 1.0, v14, 1.0
	s_movk_i32 s0, 0x3fff
	v_fma_f32 v18, -v15, v17, 1.0
	v_fmac_f32_e32 v17, v18, v17
	v_mul_f32_e32 v18, v16, v17
	v_fma_f32 v19, -v15, v18, v16
	v_fmac_f32_e32 v18, v19, v17
	v_fma_f32 v15, -v15, v18, v16
	v_div_fmas_f32 v15, v15, v17, v18
	v_div_fixup_f32 v18, v15, v14, 1.0
	v_pk_mul_f32 v[14:15], v[18:19], v[42:43] op_sel_hi:[0,1]
	v_pk_mul_f32 v[16:17], v[18:19], v[36:37] op_sel_hi:[0,1]
	v_pk_mul_f32 v[16:17], v[32:33], v[16:17]
	v_pk_mul_f32 v[14:15], v[30:31], v[14:15]
	global_store_dwordx4 v[10:11], v[14:17], off offset:-3072
	v_pk_mul_f32 v[22:23], v[18:19], v[22:23] op_sel_hi:[0,1]
	v_pk_mul_f32 v[20:21], v[18:19], v[20:21] op_sel_hi:[0,1]
	v_cmp_lt_i32_e32 vcc, s0, v1
	s_or_b64 s[24:25], vcc, s[24:25]
	v_pk_mul_f32 v[14:15], v[44:45], v[20:21]
	v_pk_mul_f32 v[16:17], v[46:47], v[22:23]
	global_store_dwordx4 v[10:11], v[14:17], off offset:-2048
	v_lshlrev_b32_e32 v20, 16, v40
	v_and_b32_e32 v21, 0xffff0000, v40
	v_lshlrev_b32_e32 v22, 16, v41
	v_and_b32_e32 v23, 0xffff0000, v41
	v_pk_mul_f32 v[22:23], v[18:19], v[22:23] op_sel_hi:[0,1]
	v_pk_mul_f32 v[20:21], v[18:19], v[20:21] op_sel_hi:[0,1]
	v_pk_mul_f32 v[14:15], v[48:49], v[20:21]
	v_pk_mul_f32 v[16:17], v[50:51], v[22:23]
	global_store_dwordx4 v[10:11], v[14:17], off offset:-1024
	v_lshlrev_b32_e32 v20, 16, v34
	v_and_b32_e32 v21, 0xffff0000, v34
	v_lshlrev_b32_e32 v22, 16, v35
	v_and_b32_e32 v23, 0xffff0000, v35
	v_pk_mul_f32 v[22:23], v[18:19], v[22:23] op_sel_hi:[0,1]
	v_pk_mul_f32 v[18:19], v[18:19], v[20:21] op_sel_hi:[0,1]
	v_pk_mul_f32 v[14:15], v[52:53], v[18:19]
	v_pk_mul_f32 v[16:17], v[54:55], v[22:23]
	global_store_dwordx4 v[10:11], v[14:17], off
	v_lshl_add_u64 v[10:11], v[10:11], 0, s[12:13]
	s_andn2_b64 exec, exec, s[24:25]
	s_cbranch_execnz .LBB0_15

.LBB0_464:
	v_ashrrev_i32_e32 v151, 31, v150
	v_lshlrev_b64 v[6:7], 9, v[150:151]
	v_lshl_add_u64 v[38:39], v[148:149], 0, v[6:7]
	global_load_dwordx4 v[40:43], v[38:39], off
	global_load_dwordx4 v[44:47], v[38:39], off offset:1024
	global_load_dwordx4 v[48:51], v[38:39], off offset:2048
	global_load_dwordx4 v[52:55], v[38:39], off offset:3072
	v_add_co_u32_e32 v6, vcc, s12, v38
	s_movk_i32 s4, 0x3000
	s_nop 0
	v_addc_co_u32_e32 v7, vcc, 0, v39, vcc
	v_add_co_u32_e32 v8, vcc, s68, v38
	v_add_u32_e32 v151, s22, v243
	s_nop 0
	v_addc_co_u32_e32 v9, vcc, 0, v39, vcc
	v_add_co_u32_e32 v14, vcc, s4, v38
	global_load_dwordx4 v[56:59], v[8:9], off offset:-4096
	global_load_dwordx4 v[60:63], v[6:7], off offset:1024
	global_load_dwordx4 v[64:67], v[6:7], off offset:2048
	global_load_dwordx4 v[68:71], v[6:7], off offset:3072
	global_load_dwordx4 v[26:29], v[8:9], off
	global_load_dwordx4 v[18:21], v[8:9], off offset:1024
	global_load_dwordx4 v[10:13], v[8:9], off offset:2048
	s_nop 0
	global_load_dwordx4 v[6:9], v[8:9], off offset:3072
	v_addc_co_u32_e32 v15, vcc, 0, v39, vcc
	v_add_co_u32_e32 v88, vcc, s69, v38
	s_movk_i32 s4, 0x5000
	s_nop 0
	v_addc_co_u32_e32 v89, vcc, 0, v39, vcc
	global_load_dwordx4 v[34:37], v[88:89], off offset:-4096
	global_load_dwordx4 v[30:33], v[14:15], off offset:1024
	global_load_dwordx4 v[22:25], v[14:15], off offset:2048
	s_nop 0
	global_load_dwordx4 v[14:17], v[14:15], off offset:3072
	ds_read_b128 v[72:75], v151 offset:14560
	ds_read_b128 v[76:79], v151 offset:31200
	ds_read_b128 v[80:83], v151 offset:47840
	ds_read_b128 v[84:87], v151 offset:64480
	v_ashrrev_i32_e32 v157, 31, v156
	v_add_u32_e32 v150, 64, v150
	v_add_u32_e32 v243, 32, v243
	s_waitcnt vmcnt(15) lgkmcnt(3)
	v_mfma_f32_16x16x32_bf16 v[72:75], v[40:43], v[72:75], 0
	s_waitcnt lgkmcnt(2)
	v_mfma_f32_16x16x32_bf16 v[76:79], v[40:43], v[76:79], 0
	s_waitcnt lgkmcnt(1)
	v_mfma_f32_16x16x32_bf16 v[80:83], v[40:43], v[80:83], 0
	s_waitcnt lgkmcnt(0)
	v_mfma_f32_16x16x32_bf16 v[40:43], v[40:43], v[84:87], 0
	ds_read_b128 v[84:87], v151 offset:12480
	s_waitcnt vmcnt(14) lgkmcnt(0)
	v_mfma_f32_16x16x32_bf16 v[72:75], v[44:47], v[84:87], v[72:75]
	ds_read_b128 v[84:87], v151 offset:29120
	s_waitcnt lgkmcnt(0)
	v_mfma_f32_16x16x32_bf16 v[76:79], v[44:47], v[84:87], v[76:79]
	ds_read_b128 v[84:87], v151 offset:45760
	s_waitcnt lgkmcnt(0)
	v_mfma_f32_16x16x32_bf16 v[80:83], v[44:47], v[84:87], v[80:83]
	ds_read_b128 v[84:87], v151 offset:62400
	s_waitcnt lgkmcnt(0)
	v_mfma_f32_16x16x32_bf16 v[40:43], v[44:47], v[84:87], v[40:43]
	ds_read_b128 v[44:47], v151 offset:10400
	s_waitcnt vmcnt(13) lgkmcnt(0)
	v_mfma_f32_16x16x32_bf16 v[44:47], v[48:51], v[44:47], v[72:75]
	s_nop 2
	ds_read_b128 v[72:75], v151 offset:27040
	s_waitcnt lgkmcnt(0)
	v_mfma_f32_16x16x32_bf16 v[72:75], v[48:51], v[72:75], v[76:79]
	s_nop 2
	ds_read_b128 v[76:79], v151 offset:43680
	s_waitcnt lgkmcnt(0)
	v_mfma_f32_16x16x32_bf16 v[76:79], v[48:51], v[76:79], v[80:83]
	s_nop 2
	ds_read_b128 v[80:83], v151 offset:60320
	s_waitcnt lgkmcnt(0)
	v_mfma_f32_16x16x32_bf16 v[40:43], v[48:51], v[80:83], v[40:43]
	ds_read_b128 v[48:51], v151 offset:8320
	s_waitcnt vmcnt(12) lgkmcnt(0)
	v_mfma_f32_16x16x32_bf16 v[44:47], v[52:55], v[48:51], v[44:47]
	ds_read_b128 v[48:51], v151 offset:24960
	s_waitcnt lgkmcnt(0)
	v_mfma_f32_16x16x32_bf16 v[48:51], v[52:55], v[48:51], v[72:75]
	s_nop 2
	ds_read_b128 v[72:75], v151 offset:41600
	s_waitcnt lgkmcnt(0)
	v_mfma_f32_16x16x32_bf16 v[72:75], v[52:55], v[72:75], v[76:79]
	s_nop 2
	ds_read_b128 v[76:79], v151 offset:58240
	s_waitcnt lgkmcnt(0)
	v_mfma_f32_16x16x32_bf16 v[40:43], v[52:55], v[76:79], v[40:43]
	ds_read_b128 v[52:55], v151 offset:6240
	s_waitcnt vmcnt(11) lgkmcnt(0)
	v_mfma_f32_16x16x32_bf16 v[44:47], v[56:59], v[52:55], v[44:47]
	ds_read_b128 v[52:55], v151 offset:22880
	s_waitcnt lgkmcnt(0)
	v_mfma_f32_16x16x32_bf16 v[48:51], v[56:59], v[52:55], v[48:51]
	ds_read_b128 v[52:55], v151 offset:39520
	s_waitcnt lgkmcnt(0)
	v_mfma_f32_16x16x32_bf16 v[52:55], v[56:59], v[52:55], v[72:75]
	s_nop 2
	ds_read_b128 v[72:75], v151 offset:56160
	s_waitcnt lgkmcnt(0)
	v_mfma_f32_16x16x32_bf16 v[40:43], v[56:59], v[72:75], v[40:43]
	ds_read_b128 v[56:59], v151 offset:4160
	s_waitcnt vmcnt(10) lgkmcnt(0)
	v_mfma_f32_16x16x32_bf16 v[44:47], v[60:63], v[56:59], v[44:47]
	ds_read_b128 v[56:59], v151 offset:20800
	s_waitcnt lgkmcnt(0)
	v_mfma_f32_16x16x32_bf16 v[48:51], v[60:63], v[56:59], v[48:51]
	ds_read_b128 v[56:59], v151 offset:37440
	s_waitcnt lgkmcnt(0)
	v_mfma_f32_16x16x32_bf16 v[52:55], v[60:63], v[56:59], v[52:55]
	ds_read_b128 v[56:59], v151 offset:54080
	s_waitcnt lgkmcnt(0)
	v_mfma_f32_16x16x32_bf16 v[40:43], v[60:63], v[56:59], v[40:43]
	ds_read_b128 v[56:59], v151 offset:2080
	s_waitcnt vmcnt(9) lgkmcnt(0)
	v_mfma_f32_16x16x32_bf16 v[44:47], v[64:67], v[56:59], v[44:47]
	ds_read_b128 v[56:59], v151 offset:18720
	s_waitcnt lgkmcnt(0)
	v_mfma_f32_16x16x32_bf16 v[48:51], v[64:67], v[56:59], v[48:51]
	ds_read_b128 v[56:59], v151 offset:35360
	s_waitcnt lgkmcnt(0)
	v_mfma_f32_16x16x32_bf16 v[58:61], v[64:67], v[56:59], v[52:55]
	s_nop 2
	ds_read_b128 v[52:55], v151 offset:52000
	s_waitcnt lgkmcnt(0)
	v_mfma_f32_16x16x32_bf16 v[40:43], v[64:67], v[52:55], v[40:43]
	ds_read_b128 v[52:55], v151
	s_waitcnt vmcnt(8) lgkmcnt(0)
	v_mfma_f32_16x16x32_bf16 v[54:57], v[68:71], v[52:55], v[44:47]
	v_add_co_u32_e32 v52, vcc, s4, v38
	s_nop 1
	ds_read_b128 v[44:47], v151 offset:16640
	s_waitcnt lgkmcnt(0)
	v_mfma_f32_16x16x32_bf16 v[44:47], v[68:71], v[44:47], v[48:51]
	s_nop 2
	ds_read_b128 v[48:51], v151 offset:33280
	v_addc_co_u32_e32 v53, vcc, 0, v39, vcc
	s_waitcnt lgkmcnt(0)
	v_mfma_f32_16x16x32_bf16 v[48:51], v[68:71], v[48:51], v[58:61]
	v_add_co_u32_e32 v102, vcc, s70, v38
	s_nop 1
	ds_read_b128 v[58:61], v151 offset:49920
	v_addc_co_u32_e32 v103, vcc, 0, v39, vcc
	s_waitcnt lgkmcnt(0)
	v_mfma_f32_16x16x32_bf16 v[40:43], v[68:71], v[58:61], v[40:43]
	global_load_dwordx4 v[70:73], v[88:89], off
	global_load_dwordx4 v[66:69], v[88:89], off offset:1024
	global_load_dwordx4 v[62:65], v[88:89], off offset:2048
	global_load_dwordx4 v[58:61], v[88:89], off offset:3072
	s_nop 0
	global_load_dwordx4 v[86:89], v[102:103], off offset:-4096
	global_load_dwordx4 v[82:85], v[52:53], off offset:1024
	global_load_dwordx4 v[78:81], v[52:53], off offset:2048
	global_load_dwordx4 v[74:77], v[52:53], off offset:3072
	ds_read_b128 v[90:93], v151 offset:14560
	s_waitcnt vmcnt(15) lgkmcnt(0)
	v_mfma_f32_16x16x32_bf16 v[44:47], v[26:29], v[90:93], v[44:47]
	ds_read_b128 v[90:93], v151 offset:31200
	s_movk_i32 s4, 0x7000
	s_waitcnt lgkmcnt(0)
	v_mfma_f32_16x16x32_bf16 v[48:51], v[26:29], v[90:93], v[48:51]
	ds_read_b128 v[90:93], v151 offset:47840
	s_waitcnt lgkmcnt(0)
	v_mfma_f32_16x16x32_bf16 v[26:29], v[26:29], v[90:93], v[40:43]
	s_nop 2
	ds_read_b128 v[40:43], v151 offset:12480
	s_waitcnt vmcnt(14) lgkmcnt(0)
	v_mfma_f32_16x16x32_bf16 v[40:43], v[18:21], v[40:43], v[44:47]
	s_nop 2
	ds_read_b128 v[44:47], v151 offset:29120
	s_waitcnt lgkmcnt(0)
	v_mfma_f32_16x16x32_bf16 v[44:47], v[18:21], v[44:47], v[48:51]
	s_nop 2
	ds_read_b128 v[48:51], v151 offset:45760
	s_waitcnt lgkmcnt(0)
	v_mfma_f32_16x16x32_bf16 v[18:21], v[18:21], v[48:51], v[26:29]
	s_nop 2
	ds_read_b128 v[26:29], v151 offset:10400
	s_waitcnt vmcnt(13) lgkmcnt(0)
	v_mfma_f32_16x16x32_bf16 v[26:29], v[10:13], v[26:29], v[40:43]
	s_nop 2
	ds_read_b128 v[40:43], v151 offset:27040
	s_waitcnt lgkmcnt(0)
	v_mfma_f32_16x16x32_bf16 v[40:43], v[10:13], v[40:43], v[44:47]
	s_nop 2
	ds_read_b128 v[44:47], v151 offset:43680
	s_waitcnt lgkmcnt(0)
	v_mfma_f32_16x16x32_bf16 v[10:13], v[10:13], v[44:47], v[18:21]
	s_nop 2
	ds_read_b128 v[18:21], v151 offset:8320
	s_waitcnt vmcnt(12) lgkmcnt(0)
	v_mfma_f32_16x16x32_bf16 v[18:21], v[6:9], v[18:21], v[26:29]
	s_nop 2
	ds_read_b128 v[26:29], v151 offset:24960
	s_waitcnt lgkmcnt(0)
	v_mfma_f32_16x16x32_bf16 v[26:29], v[6:9], v[26:29], v[40:43]
	s_nop 2
	ds_read_b128 v[40:43], v151 offset:41600
	s_waitcnt lgkmcnt(0)
	v_mfma_f32_16x16x32_bf16 v[6:9], v[6:9], v[40:43], v[10:13]
	s_nop 2
	ds_read_b128 v[10:13], v151 offset:6240
	s_waitcnt vmcnt(11) lgkmcnt(0)
	v_mfma_f32_16x16x32_bf16 v[10:13], v[34:37], v[10:13], v[18:21]
	s_nop 2
	ds_read_b128 v[18:21], v151 offset:22880
	s_waitcnt lgkmcnt(0)
	v_mfma_f32_16x16x32_bf16 v[18:21], v[34:37], v[18:21], v[26:29]
	s_nop 2
	ds_read_b128 v[26:29], v151 offset:39520
	s_waitcnt lgkmcnt(0)
	v_mfma_f32_16x16x32_bf16 v[6:9], v[34:37], v[26:29], v[6:9]
	ds_read_b128 v[26:29], v151 offset:4160
	s_waitcnt vmcnt(10) lgkmcnt(0)
	v_mfma_f32_16x16x32_bf16 v[10:13], v[30:33], v[26:29], v[10:13]
	ds_read_b128 v[26:29], v151 offset:20800
	s_waitcnt lgkmcnt(0)
	v_mfma_f32_16x16x32_bf16 v[18:21], v[30:33], v[26:29], v[18:21]
	ds_read_b128 v[26:29], v151 offset:37440
	s_waitcnt lgkmcnt(0)
	v_mfma_f32_16x16x32_bf16 v[6:9], v[30:33], v[26:29], v[6:9]
	ds_read_b128 v[26:29], v151 offset:2080
	s_waitcnt vmcnt(9) lgkmcnt(0)
	v_mfma_f32_16x16x32_bf16 v[10:13], v[22:25], v[26:29], v[10:13]
	ds_read_b128 v[26:29], v151 offset:18720
	s_waitcnt lgkmcnt(0)
	v_mfma_f32_16x16x32_bf16 v[18:21], v[22:25], v[26:29], v[18:21]
	ds_read_b128 v[26:29], v151 offset:35360
	s_waitcnt lgkmcnt(0)
	v_mfma_f32_16x16x32_bf16 v[6:9], v[22:25], v[26:29], v[6:9]
	ds_read_b128 v[22:25], v151
	v_lshl_add_u64 v[26:27], v[156:157], 3, s[0:1]
	v_add_u32_e32 v156, 64, v156
	s_waitcnt vmcnt(8) lgkmcnt(0)
	v_mfma_f32_16x16x32_bf16 v[50:53], v[14:17], v[22:25], v[10:13]
	s_nop 2
	ds_read_b128 v[10:13], v151 offset:16640
	s_waitcnt lgkmcnt(0)
	v_mfma_f32_16x16x32_bf16 v[106:109], v[14:17], v[10:13], v[18:21]
	ds_read_b128 v[10:13], v151 offset:33280
	global_load_dwordx4 v[90:93], v[102:103], off
	global_load_dwordx4 v[94:97], v[102:103], off offset:1024
	global_load_dwordx4 v[98:101], v[102:103], off offset:2048
	s_nop 0
	global_load_dwordx4 v[102:105], v[102:103], off offset:3072
	s_waitcnt lgkmcnt(0)
	v_mfma_f32_16x16x32_bf16 v[110:113], v[14:17], v[10:13], v[6:9]
	s_nop 2
	v_add_co_u32_e32 v6, vcc, s4, v38
	v_add_u32_e32 v8, s23, v239
	s_nop 0
	v_addc_co_u32_e32 v7, vcc, 0, v39, vcc
	global_load_dwordx4 v[118:121], v[6:7], off
	global_load_dwordx4 v[122:125], v[6:7], off offset:1024
	global_load_dwordx4 v[126:129], v[6:7], off offset:2048
	global_load_dwordx4 v[130:133], v[6:7], off offset:3072
	global_load_dwordx4 v[46:49], v[152:153], off offset:-128
	v_add_u32_e32 v6, s23, v240
	v_ashrrev_i32_e32 v7, 31, v6
	v_lshl_add_u64 v[10:11], v[6:7], 3, s[96:97]
	v_ashrrev_i32_e32 v9, 31, v8
	global_load_dwordx2 v[218:219], v[10:11], off offset:8
	v_lshl_add_u64 v[10:11], v[8:9], 3, s[96:97]
	global_load_dwordx2 v[208:209], v[10:11], off offset:128
	v_add_u32_e32 v10, 17, v8
	v_add_u32_e32 v12, 17, v6
	v_ashrrev_i32_e32 v13, 31, v12
	v_ashrrev_i32_e32 v11, 31, v10
	v_lshl_add_u64 v[12:13], v[12:13], 3, s[96:97]
	v_lshl_add_u64 v[10:11], v[10:11], 3, s[96:97]
	global_load_dwordx4 v[114:117], v[26:27], off offset:16
	global_load_dwordx4 v[134:137], v[26:27], off
	global_load_dwordx2 v[214:215], v[12:13], off offset:8
	global_load_dwordx2 v[206:207], v[10:11], off offset:128
	v_add_u32_e32 v10, 34, v8
	v_add_u32_e32 v12, 34, v6
	v_ashrrev_i32_e32 v13, 31, v12
	v_ashrrev_i32_e32 v11, 31, v10
	v_lshl_add_u64 v[12:13], v[12:13], 3, s[96:97]
	v_lshl_add_u64 v[10:11], v[10:11], 3, s[96:97]
	global_load_dwordx2 v[220:221], v[12:13], off offset:8
	global_load_dwordx2 v[212:213], v[10:11], off offset:128
	v_add_u32_e32 v10, 51, v8
	v_add_u32_e32 v12, 51, v6
	v_ashrrev_i32_e32 v13, 31, v12
	v_ashrrev_i32_e32 v11, 31, v10
	v_lshl_add_u64 v[12:13], v[12:13], 3, s[96:97]
	v_lshl_add_u64 v[10:11], v[10:11], 3, s[96:97]
	global_load_dwordx2 v[216:217], v[12:13], off offset:8
	global_load_dwordx2 v[210:211], v[10:11], off offset:128
	global_load_dwordx4 v[34:37], v[152:153], off offset:-64
	v_add_u32_e32 v10, 0x110, v8
	v_add_u32_e32 v12, 0x110, v6
	v_ashrrev_i32_e32 v13, 31, v12
	v_ashrrev_i32_e32 v11, 31, v10
	v_lshl_add_u64 v[12:13], v[12:13], 3, s[96:97]
	v_lshl_add_u64 v[10:11], v[10:11], 3, s[96:97]
	global_load_dwordx2 v[202:203], v[12:13], off offset:8
	global_load_dwordx2 v[192:193], v[10:11], off offset:128
	global_load_dwordx4 v[38:41], v[26:27], off offset:144
	global_load_dwordx4 v[42:45], v[26:27], off offset:128
	v_add_u32_e32 v10, 0x121, v8
	v_add_u32_e32 v12, 0x121, v6
	v_ashrrev_i32_e32 v13, 31, v12
	v_ashrrev_i32_e32 v11, 31, v10
	v_lshl_add_u64 v[12:13], v[12:13], 3, s[96:97]
	v_lshl_add_u64 v[10:11], v[10:11], 3, s[96:97]
	global_load_dwordx2 v[198:199], v[12:13], off offset:8
	global_load_dwordx2 v[190:191], v[10:11], off offset:128
	v_add_u32_e32 v10, 0x132, v8
	v_add_u32_e32 v12, 0x132, v6
	v_ashrrev_i32_e32 v13, 31, v12
	v_ashrrev_i32_e32 v11, 31, v10
	v_lshl_add_u64 v[12:13], v[12:13], 3, s[96:97]
	v_lshl_add_u64 v[10:11], v[10:11], 3, s[96:97]
	global_load_dwordx2 v[204:205], v[12:13], off offset:8
	global_load_dwordx2 v[196:197], v[10:11], off offset:128
	v_add_u32_e32 v10, 0x143, v8
	v_add_u32_e32 v12, 0x143, v6
	v_ashrrev_i32_e32 v13, 31, v12
	v_ashrrev_i32_e32 v11, 31, v10
	v_lshl_add_u64 v[12:13], v[12:13], 3, s[96:97]
	v_lshl_add_u64 v[10:11], v[10:11], 3, s[96:97]
	global_load_dwordx2 v[200:201], v[12:13], off offset:8
	global_load_dwordx2 v[194:195], v[10:11], off offset:128
	global_load_dwordx4 v[14:17], v[152:153], off
	v_add_u32_e32 v10, 0x220, v8
	v_add_u32_e32 v12, 0x220, v6
	v_ashrrev_i32_e32 v13, 31, v12
	v_ashrrev_i32_e32 v11, 31, v10
	v_lshl_add_u64 v[12:13], v[12:13], 3, s[96:97]
	v_lshl_add_u64 v[10:11], v[10:11], 3, s[96:97]
	global_load_dwordx2 v[184:185], v[12:13], off offset:8
	global_load_dwordx2 v[178:179], v[10:11], off offset:128
	global_load_dwordx4 v[22:25], v[26:27], off offset:272
	global_load_dwordx4 v[30:33], v[26:27], off offset:256
	v_add_u32_e32 v10, 0x231, v8
	v_add_u32_e32 v12, 0x231, v6
	v_ashrrev_i32_e32 v13, 31, v12
	v_ashrrev_i32_e32 v11, 31, v10
	v_lshl_add_u64 v[12:13], v[12:13], 3, s[96:97]
	v_lshl_add_u64 v[10:11], v[10:11], 3, s[96:97]
	global_load_dwordx2 v[182:183], v[12:13], off offset:8
	global_load_dwordx2 v[172:173], v[10:11], off offset:128
	v_add_u32_e32 v10, 0x242, v8
	v_add_u32_e32 v12, 0x242, v6
	v_ashrrev_i32_e32 v13, 31, v12
	v_ashrrev_i32_e32 v11, 31, v10
	v_lshl_add_u64 v[12:13], v[12:13], 3, s[96:97]
	v_lshl_add_u64 v[10:11], v[10:11], 3, s[96:97]
	global_load_dwordx2 v[186:187], v[12:13], off offset:8
	global_load_dwordx2 v[180:181], v[10:11], off offset:128
	v_add_u32_e32 v10, 0x253, v8
	v_add_u32_e32 v12, 0x253, v6
	v_add_u32_e32 v18, 0x330, v8
	v_add_u32_e32 v20, 0x330, v6
	v_add_u32_e32 v140, 0x341, v8
	v_add_u32_e32 v142, 0x341, v6
	v_ashrrev_i32_e32 v13, 31, v12
	v_ashrrev_i32_e32 v11, 31, v10
	v_ashrrev_i32_e32 v21, 31, v20
	v_ashrrev_i32_e32 v19, 31, v18
	v_ashrrev_i32_e32 v143, 31, v142
	v_ashrrev_i32_e32 v141, 31, v140
	v_lshl_add_u64 v[12:13], v[12:13], 3, s[96:97]
	v_lshl_add_u64 v[10:11], v[10:11], 3, s[96:97]
	v_lshl_add_u64 v[20:21], v[20:21], 3, s[96:97]
	v_lshl_add_u64 v[18:19], v[18:19], 3, s[96:97]
	v_lshl_add_u64 v[142:143], v[142:143], 3, s[96:97]
	v_lshl_add_u64 v[140:141], v[140:141], 3, s[96:97]
	global_load_dwordx2 v[176:177], v[12:13], off offset:8
	global_load_dwordx2 v[170:171], v[10:11], off offset:128
	s_nop 0
	global_load_dwordx4 v[10:13], v[152:153], off offset:64
	global_load_dwordx2 v[162:163], v[20:21], off offset:8
	global_load_dwordx2 v[160:161], v[18:19], off offset:128
	s_nop 0
	global_load_dwordx4 v[18:21], v[26:27], off offset:400
	s_nop 0
	global_load_dwordx4 v[26:29], v[26:27], off offset:384
	s_addk_i32 s23, 0x440
	global_load_dwordx2 v[164:165], v[142:143], off offset:8
	global_load_dwordx2 v[158:159], v[140:141], off offset:128
	v_add_u32_e32 v142, 0x352, v6
	v_add_u32_e32 v6, 0x363, v6
	v_ashrrev_i32_e32 v7, 31, v6
	v_lshl_add_u64 v[6:7], v[6:7], 3, s[96:97]
	global_load_dwordx2 v[174:175], v[6:7], off offset:8
	v_add_u32_e32 v140, 0x352, v8
	v_add_u32_e32 v8, 0x363, v8
	v_ashrrev_i32_e32 v143, 31, v142
	v_ashrrev_i32_e32 v141, 31, v140
	v_ashrrev_i32_e32 v9, 31, v8
	v_lshl_add_u64 v[142:143], v[142:143], 3, s[96:97]
	v_lshl_add_u64 v[140:141], v[140:141], 3, s[96:97]
	v_lshl_add_u64 v[6:7], v[8:9], 3, s[96:97]
	global_load_dwordx2 v[168:169], v[142:143], off offset:8
	global_load_dwordx2 v[166:167], v[140:141], off offset:128
	global_load_dwordx2 v[188:189], v[6:7], off offset:128
	s_nop 0
	global_load_dwordx4 v[6:9], v[154:155], off
	ds_read_b128 v[244:247], v151 offset:14560
	ds_read_b128 v[140:143], v151 offset:31200
	s_waitcnt vmcnt(60) lgkmcnt(1)
	v_mfma_f32_16x16x32_bf16 v[106:109], v[70:73], v[244:247], v[106:109]
	v_lshl_add_u64 v[152:153], v[152:153], 0, s[14:15]
	v_lshl_add_u64 v[154:155], v[154:155], 0, 64
	s_cmpk_eq_i32 s23, 0x1100
	s_waitcnt lgkmcnt(0)
	v_mfma_f32_16x16x32_bf16 v[70:73], v[70:73], v[140:143], v[110:113]
	ds_read_b128 v[140:143], v151 offset:29120
	s_nop 1
	ds_read_b128 v[110:113], v151 offset:12480
	s_waitcnt vmcnt(59) lgkmcnt(0)
	v_mfma_f32_16x16x32_bf16 v[106:109], v[66:69], v[110:113], v[106:109]
	v_mfma_f32_16x16x32_bf16 v[66:69], v[66:69], v[140:143], v[70:73]
	ds_read_b128 v[140:143], v151 offset:27040
	s_nop 1
	ds_read_b128 v[70:73], v151 offset:10400
	s_waitcnt vmcnt(58) lgkmcnt(0)
	v_mfma_f32_16x16x32_bf16 v[106:109], v[62:65], v[70:73], v[106:109]
	v_mfma_f32_16x16x32_bf16 v[62:65], v[62:65], v[140:143], v[66:69]
	ds_read_b128 v[140:143], v151 offset:24960
	s_nop 1
	ds_read_b128 v[66:69], v151 offset:8320
	s_waitcnt vmcnt(57) lgkmcnt(0)
	v_mfma_f32_16x16x32_bf16 v[106:109], v[58:61], v[66:69], v[106:109]
	v_mfma_f32_16x16x32_bf16 v[58:61], v[58:61], v[140:143], v[62:65]
	ds_read_b128 v[140:143], v151 offset:6240
	s_waitcnt vmcnt(56) lgkmcnt(0)
	v_mfma_f32_16x16x32_bf16 v[62:65], v[86:89], v[140:143], v[106:109]
	s_nop 3
	ds_read_b128 v[106:109], v151 offset:22880
	s_waitcnt lgkmcnt(0)
	v_mfma_f32_16x16x32_bf16 v[58:61], v[86:89], v[106:109], v[58:61]
	ds_read_b128 v[86:89], v151 offset:4160
	ds_read_b128 v[106:109], v151 offset:20800
	s_waitcnt vmcnt(55) lgkmcnt(1)
	v_mfma_f32_16x16x32_bf16 v[62:65], v[82:85], v[86:89], v[62:65]
	s_waitcnt lgkmcnt(0)
	v_mfma_f32_16x16x32_bf16 v[58:61], v[82:85], v[106:109], v[58:61]
	ds_read_b128 v[82:85], v151 offset:2080
	ds_read_b128 v[106:109], v151 offset:18720
	s_waitcnt vmcnt(54) lgkmcnt(1)
	v_mfma_f32_16x16x32_bf16 v[62:65], v[78:81], v[82:85], v[62:65]
	s_waitcnt lgkmcnt(0)
	v_mfma_f32_16x16x32_bf16 v[58:61], v[78:81], v[106:109], v[58:61]
	ds_read_b128 v[78:81], v151
	ds_read_b128 v[106:109], v151 offset:16640
	s_waitcnt vmcnt(53) lgkmcnt(0)
	v_mfma_f32_16x16x32_bf16 v[58:61], v[74:77], v[106:109], v[58:61]
	s_waitcnt vmcnt(52)
	v_mfma_f32_16x16x32_bf16 v[58:61], v[90:93], v[244:247], v[58:61]
	s_waitcnt vmcnt(51)
	v_mfma_f32_16x16x32_bf16 v[58:61], v[94:97], v[110:113], v[58:61]
	s_waitcnt vmcnt(50)
	v_mfma_f32_16x16x32_bf16 v[58:61], v[98:101], v[70:73], v[58:61]
	s_waitcnt vmcnt(40)
	v_mov_b32_e32 v72, v134
	v_mov_b32_e32 v73, v136
	v_mov_b32_e32 v70, v114
	v_mfma_f32_16x16x32_bf16 v[58:61], v[102:105], v[66:69], v[58:61]
	v_mov_b32_e32 v71, v116
	v_mov_b32_e32 v136, v135
	v_mov_b32_e32 v116, v115
	v_mfma_f32_16x16x32_bf16 v[58:61], v[118:121], v[140:143], v[58:61]
	v_mfma_f32_16x16x32_bf16 v[58:61], v[122:125], v[86:89], v[58:61]
	v_mfma_f32_16x16x32_bf16 v[58:61], v[126:129], v[82:85], v[58:61]
	v_mfma_f32_16x16x32_bf16 v[62:65], v[74:77], v[78:81], v[62:65]
	s_waitcnt vmcnt(39)
	v_mov_b32_e32 v75, v214
	v_mov_b32_e32 v214, v219
	s_waitcnt vmcnt(35)
	v_mov_b32_e32 v77, v216
	v_mov_b32_e32 v216, v221
	v_mfma_f32_16x16x32_bf16 v[66:69], v[130:133], v[78:81], v[58:61]
	v_mov_b32_e32 v74, v218
	v_mov_b32_e32 v76, v220
	v_pk_mul_f32 v[80:81], v[216:217], v[70:71]
	v_pk_mul_f32 v[60:61], v[214:215], v[72:73]
	v_pk_mul_f32 v[58:59], v[214:215], v[136:137]
	v_pk_fma_f32 v[60:61], v[74:75], v[136:137], v[60:61]
	v_pk_mul_f32 v[78:79], v[216:217], v[116:117]
	v_pk_fma_f32 v[80:81], v[76:77], v[116:117], v[80:81]
	v_pk_fma_f32 v[58:59], v[74:75], v[72:73], v[58:59] neg_lo:[0,0,1] neg_hi:[0,0,1]
	v_pk_fma_f32 v[78:79], v[76:77], v[70:71], v[78:79] neg_lo:[0,0,1] neg_hi:[0,0,1]
	v_cvt_pk_bf16_f32 v59, v59, v61
	v_cvt_pk_bf16_f32 v61, v79, v81
	v_cvt_pk_bf16_f32 v58, v58, v60
	v_cvt_pk_bf16_f32 v60, v78, v80
	v_mov_b32_e32 v79, v206
	v_mov_b32_e32 v206, v209
	v_mfma_f32_16x16x32_bf16 v[54:57], v[46:49], v[58:61], v[54:57]
	v_mov_b32_e32 v78, v208
	v_pk_mul_f32 v[58:59], v[214:215], v[206:207]
	v_mov_b32_e32 v82, v212
	s_waitcnt vmcnt(34)
	v_mov_b32_e32 v83, v210
	v_mov_b32_e32 v210, v213
	v_pk_fma_f32 v[80:81], v[74:75], v[78:79], v[58:59] neg_lo:[0,0,1] neg_hi:[0,0,1]
	v_pk_mul_f32 v[58:59], v[214:215], v[78:79]
	v_pk_mul_f32 v[84:85], v[216:217], v[210:211]
	v_pk_mul_f32 v[86:87], v[216:217], v[82:83]
	v_pk_fma_f32 v[74:75], v[74:75], v[206:207], v[58:59]
	v_pk_fma_f32 v[84:85], v[76:77], v[82:83], v[84:85] neg_lo:[0,0,1] neg_hi:[0,0,1]
	v_pk_fma_f32 v[76:77], v[76:77], v[210:211], v[86:87]
	v_pk_mul_f32 v[60:61], v[72:73], v[74:75]
	v_pk_mul_f32 v[88:89], v[70:71], v[76:77]
	v_pk_mul_f32 v[58:59], v[136:137], v[74:75]
	v_pk_fma_f32 v[60:61], v[136:137], v[80:81], v[60:61]
	v_pk_mul_f32 v[86:87], v[116:117], v[76:77]
	v_pk_fma_f32 v[88:89], v[116:117], v[84:85], v[88:89]
	v_pk_fma_f32 v[58:59], v[72:73], v[80:81], v[58:59] neg_lo:[0,0,1] neg_hi:[0,0,1]
	v_pk_fma_f32 v[86:87], v[70:71], v[84:85], v[86:87] neg_lo:[0,0,1] neg_hi:[0,0,1]
	v_cvt_pk_bf16_f32 v59, v59, v61
	v_cvt_pk_bf16_f32 v61, v87, v89
	v_cvt_pk_bf16_f32 v58, v58, v60
	v_cvt_pk_bf16_f32 v60, v86, v88
	s_nop 1
	v_mfma_f32_16x16x32_bf16 v[58:61], v[46:49], v[58:61], v[50:53]
	s_nop 2
	v_mul_f32_e64 v52, v78, v74
	v_mul_f32_e64 v53, v79, v75
	v_pk_mul_f32 v[50:51], v[206:207], v[74:75]
	v_pk_fma_f32 v[52:53], v[206:207], v[80:81], v[52:53]
	v_pk_fma_f32 v[50:51], v[78:79], v[80:81], v[50:51] neg_lo:[0,0,1] neg_hi:[0,0,1]
	v_pk_mul_f32 v[74:75], v[136:137], v[52:53]
	v_pk_mul_f32 v[80:81], v[72:73], v[52:53]
	v_pk_mul_f32 v[86:87], v[206:207], v[52:53]
	v_pk_mul_f32 v[52:53], v[78:79], v[52:53]
	v_pk_fma_f32 v[74:75], v[72:73], v[50:51], v[74:75] neg_lo:[0,0,1] neg_hi:[0,0,1]
	v_pk_fma_f32 v[80:81], v[136:137], v[50:51], v[80:81]
	v_pk_fma_f32 v[86:87], v[78:79], v[50:51], v[86:87] neg_lo:[0,0,1] neg_hi:[0,0,1]
	v_pk_fma_f32 v[50:51], v[206:207], v[50:51], v[52:53]
	s_nop 0
	v_pk_mul_f32 v[52:53], v[136:137], v[50:51]
	v_pk_mul_f32 v[50:51], v[72:73], v[50:51]
	v_pk_fma_f32 v[78:79], v[72:73], v[86:87], v[52:53] neg_lo:[0,0,1] neg_hi:[0,0,1]
	v_pk_mul_f32 v[52:53], v[82:83], v[76:77]
	v_pk_fma_f32 v[72:73], v[136:137], v[86:87], v[50:51]
	v_pk_mul_f32 v[50:51], v[210:211], v[76:77]
	v_pk_fma_f32 v[52:53], v[210:211], v[84:85], v[52:53]
	v_pk_fma_f32 v[50:51], v[82:83], v[84:85], v[50:51] neg_lo:[0,0,1] neg_hi:[0,0,1]
	v_pk_mul_f32 v[84:85], v[70:71], v[52:53]
	v_pk_mul_f32 v[76:77], v[116:117], v[52:53]
	v_pk_fma_f32 v[84:85], v[116:117], v[50:51], v[84:85]
	v_pk_mul_f32 v[86:87], v[210:211], v[52:53]
	v_pk_mul_f32 v[52:53], v[82:83], v[52:53]
	v_pk_fma_f32 v[76:77], v[70:71], v[50:51], v[76:77] neg_lo:[0,0,1] neg_hi:[0,0,1]
	v_pk_fma_f32 v[86:87], v[82:83], v[50:51], v[86:87] neg_lo:[0,0,1] neg_hi:[0,0,1]
	v_pk_fma_f32 v[82:83], v[210:211], v[50:51], v[52:53]
	v_cvt_pk_bf16_f32 v53, v77, v85
	v_cvt_pk_bf16_f32 v52, v76, v84
	v_cvt_pk_bf16_f32 v51, v75, v81
	v_cvt_pk_bf16_f32 v50, v74, v80
	s_nop 1
	v_mfma_f32_16x16x32_bf16 v[62:65], v[46:49], v[50:53], v[62:65]
	v_mul_f32_e64 v52, v70, v82
	v_mul_f32_e64 v53, v71, v83
	v_pk_mul_f32 v[50:51], v[116:117], v[82:83]
	v_pk_fma_f32 v[52:53], v[116:117], v[86:87], v[52:53]
	v_pk_fma_f32 v[50:51], v[70:71], v[86:87], v[50:51] neg_lo:[0,0,1] neg_hi:[0,0,1]
	s_nop 0
	v_cvt_pk_bf16_f32 v53, v51, v53
	v_cvt_pk_bf16_f32 v51, v79, v73
	v_cvt_pk_bf16_f32 v52, v50, v52
	v_cvt_pk_bf16_f32 v50, v78, v72
	s_waitcnt vmcnt(28)
	v_mov_b32_e32 v75, v198
	v_mov_b32_e32 v70, v42
	v_mov_b32_e32 v71, v44
	v_mov_b32_e32 v198, v203
	s_waitcnt vmcnt(24)
	v_mov_b32_e32 v77, v200
	v_mov_b32_e32 v72, v38
	v_mov_b32_e32 v73, v40
	v_mov_b32_e32 v200, v205
	v_mfma_f32_16x16x32_bf16 v[66:69], v[46:49], v[50:53], v[66:69]
	v_mov_b32_e32 v74, v202
	v_mov_b32_e32 v44, v43
	v_pk_mul_f32 v[46:47], v[198:199], v[70:71]
	v_mov_b32_e32 v76, v204
	v_mov_b32_e32 v40, v39
	v_pk_mul_f32 v[48:49], v[200:201], v[72:73]
	v_pk_mul_f32 v[42:43], v[198:199], v[44:45]
	v_pk_fma_f32 v[46:47], v[74:75], v[44:45], v[46:47]
	v_pk_mul_f32 v[38:39], v[200:201], v[40:41]
	v_pk_fma_f32 v[48:49], v[76:77], v[40:41], v[48:49]
	v_pk_fma_f32 v[42:43], v[74:75], v[70:71], v[42:43] neg_lo:[0,0,1] neg_hi:[0,0,1]
	v_pk_fma_f32 v[38:39], v[76:77], v[72:73], v[38:39] neg_lo:[0,0,1] neg_hi:[0,0,1]
	s_nop 0
	v_cvt_pk_bf16_f32 v49, v39, v49
	v_cvt_pk_bf16_f32 v48, v38, v48
	v_cvt_pk_bf16_f32 v47, v43, v47
	v_cvt_pk_bf16_f32 v46, v42, v46
	v_mov_b32_e32 v38, v192
	v_mov_b32_e32 v39, v190
	v_mov_b32_e32 v190, v193
	v_mfma_f32_16x16x32_bf16 v[50:53], v[34:37], v[46:49], v[54:57]
	v_mul_f32_e64 v42, v198, v190
	v_mul_f32_e64 v43, v199, v191
	v_pk_mul_f32 v[46:47], v[198:199], v[38:39]
	v_pk_fma_f32 v[42:43], v[74:75], v[38:39], v[42:43] neg_lo:[0,0,1] neg_hi:[0,0,1]
	v_mov_b32_e32 v56, v196
	s_waitcnt vmcnt(23)
	v_mov_b32_e32 v57, v194
	v_mov_b32_e32 v194, v197
	v_pk_fma_f32 v[54:55], v[74:75], v[190:191], v[46:47]
	v_pk_mul_f32 v[74:75], v[200:201], v[194:195]
	v_pk_mul_f32 v[78:79], v[200:201], v[56:57]
	v_pk_fma_f32 v[74:75], v[76:77], v[56:57], v[74:75] neg_lo:[0,0,1] neg_hi:[0,0,1]
	v_pk_fma_f32 v[76:77], v[76:77], v[194:195], v[78:79]
	v_pk_mul_f32 v[48:49], v[70:71], v[54:55]
	v_pk_mul_f32 v[80:81], v[72:73], v[76:77]
	v_pk_mul_f32 v[46:47], v[44:45], v[54:55]
	v_pk_fma_f32 v[48:49], v[44:45], v[42:43], v[48:49]
	v_pk_mul_f32 v[78:79], v[40:41], v[76:77]
	v_pk_fma_f32 v[80:81], v[40:41], v[74:75], v[80:81]
	v_pk_fma_f32 v[46:47], v[70:71], v[42:43], v[46:47] neg_lo:[0,0,1] neg_hi:[0,0,1]
	v_pk_fma_f32 v[78:79], v[72:73], v[74:75], v[78:79] neg_lo:[0,0,1] neg_hi:[0,0,1]
	v_cvt_pk_bf16_f32 v47, v47, v49
	v_cvt_pk_bf16_f32 v49, v79, v81
	v_cvt_pk_bf16_f32 v46, v46, v48
	v_cvt_pk_bf16_f32 v48, v78, v80
	s_nop 1
	v_mfma_f32_16x16x32_bf16 v[46:49], v[34:37], v[46:49], v[58:61]
	s_nop 2
	v_mul_f32_e64 v58, v190, v54
	v_mul_f32_e64 v59, v191, v55
	v_pk_mul_f32 v[54:55], v[38:39], v[54:55]
	v_pk_fma_f32 v[58:59], v[38:39], v[42:43], v[58:59] neg_lo:[0,0,1] neg_hi:[0,0,1]
	v_pk_fma_f32 v[42:43], v[190:191], v[42:43], v[54:55]
	s_nop 0
	v_pk_mul_f32 v[78:79], v[190:191], v[42:43]
	v_pk_mul_f32 v[54:55], v[44:45], v[42:43]
	v_pk_fma_f32 v[78:79], v[38:39], v[58:59], v[78:79] neg_lo:[0,0,1] neg_hi:[0,0,1]
	v_pk_mul_f32 v[38:39], v[38:39], v[42:43]
	v_pk_mul_f32 v[60:61], v[70:71], v[42:43]
	v_pk_fma_f32 v[38:39], v[190:191], v[58:59], v[38:39]
	v_pk_fma_f32 v[60:61], v[44:45], v[58:59], v[60:61]
	v_pk_mul_f32 v[42:43], v[44:45], v[38:39]
	v_pk_mul_f32 v[38:39], v[70:71], v[38:39]
	v_pk_fma_f32 v[54:55], v[70:71], v[58:59], v[54:55] neg_lo:[0,0,1] neg_hi:[0,0,1]
	v_pk_fma_f32 v[38:39], v[44:45], v[78:79], v[38:39]
	v_pk_mul_f32 v[44:45], v[56:57], v[76:77]
	v_pk_fma_f32 v[58:59], v[70:71], v[78:79], v[42:43] neg_lo:[0,0,1] neg_hi:[0,0,1]
	v_pk_mul_f32 v[42:43], v[194:195], v[76:77]
	v_pk_fma_f32 v[44:45], v[194:195], v[74:75], v[44:45]
	v_pk_fma_f32 v[42:43], v[56:57], v[74:75], v[42:43] neg_lo:[0,0,1] neg_hi:[0,0,1]
	v_pk_mul_f32 v[74:75], v[72:73], v[44:45]
	v_pk_mul_f32 v[70:71], v[40:41], v[44:45]
	v_pk_fma_f32 v[74:75], v[40:41], v[42:43], v[74:75]
	v_pk_mul_f32 v[76:77], v[194:195], v[44:45]
	v_pk_mul_f32 v[44:45], v[56:57], v[44:45]
	v_pk_fma_f32 v[70:71], v[72:73], v[42:43], v[70:71] neg_lo:[0,0,1] neg_hi:[0,0,1]
	v_pk_fma_f32 v[76:77], v[56:57], v[42:43], v[76:77] neg_lo:[0,0,1] neg_hi:[0,0,1]
	v_pk_fma_f32 v[56:57], v[194:195], v[42:43], v[44:45]
	v_cvt_pk_bf16_f32 v45, v71, v75
	v_cvt_pk_bf16_f32 v44, v70, v74
	v_cvt_pk_bf16_f32 v43, v55, v61
	v_cvt_pk_bf16_f32 v42, v54, v60
	v_pk_mul_f32 v[54:55], v[40:41], v[56:57]
	v_pk_mul_f32 v[56:57], v[72:73], v[56:57]
	v_pk_fma_f32 v[54:55], v[72:73], v[76:77], v[54:55] neg_lo:[0,0,1] neg_hi:[0,0,1]
	v_pk_fma_f32 v[40:41], v[40:41], v[76:77], v[56:57]
	v_cvt_pk_bf16_f32 v38, v58, v38
	v_cvt_pk_bf16_f32 v41, v55, v41
	v_cvt_pk_bf16_f32 v40, v54, v40
	v_cvt_pk_bf16_f32 v39, v59, v39
	s_waitcnt vmcnt(17)
	v_mov_b32_e32 v59, v182
	v_mov_b32_e32 v55, v32
	v_mov_b32_e32 v182, v185
	v_mov_b32_e32 v32, v31
	v_mov_b32_e32 v58, v184
	v_mov_b32_e32 v54, v30
	v_pk_mul_f32 v[30:31], v[182:183], v[32:33]
	v_mfma_f32_16x16x32_bf16 v[42:45], v[34:37], v[42:45], v[62:65]
	s_waitcnt vmcnt(13)
	v_mov_b32_e32 v57, v176
	v_mov_b32_e32 v176, v187
	v_mov_b32_e32 v56, v186
	v_mfma_f32_16x16x32_bf16 v[34:37], v[34:37], v[38:41], v[66:69]
	v_fma_f32 v38, v58, v54, -v30
	v_fma_f32 v39, v59, v55, -v31
	v_pk_mul_f32 v[30:31], v[182:183], v[54:55]
	s_nop 0
	v_pk_fma_f32 v[40:41], v[58:59], v[32:33], v[30:31]
	v_mov_b32_e32 v30, v22
	v_mov_b32_e32 v31, v24
	v_mov_b32_e32 v24, v23
	v_pk_mul_f32 v[60:61], v[176:177], v[30:31]
	v_pk_mul_f32 v[22:23], v[176:177], v[24:25]
	v_pk_fma_f32 v[60:61], v[56:57], v[24:25], v[60:61]
	v_pk_fma_f32 v[22:23], v[56:57], v[30:31], v[22:23] neg_lo:[0,0,1] neg_hi:[0,0,1]
	v_cvt_pk_bf16_f32 v39, v39, v41
	v_cvt_pk_bf16_f32 v41, v23, v61
	v_cvt_pk_bf16_f32 v38, v38, v40
	v_cvt_pk_bf16_f32 v40, v22, v60
	s_nop 1
	v_mfma_f32_16x16x32_bf16 v[38:41], v[14:17], v[38:41], v[50:53]
	s_nop 2
	v_mov_b32_e32 v51, v172
	v_mov_b32_e32 v172, v179
	v_mov_b32_e32 v50, v178
	v_pk_mul_f32 v[22:23], v[182:183], v[172:173]
	s_nop 0
	v_pk_fma_f32 v[52:53], v[58:59], v[50:51], v[22:23] neg_lo:[0,0,1] neg_hi:[0,0,1]
	v_pk_mul_f32 v[22:23], v[182:183], v[50:51]
	s_nop 0
	v_pk_fma_f32 v[58:59], v[58:59], v[172:173], v[22:23]
	s_nop 0
	v_pk_mul_f32 v[22:23], v[32:33], v[58:59]
	s_nop 0
	v_pk_fma_f32 v[60:61], v[54:55], v[52:53], v[22:23] neg_lo:[0,0,1] neg_hi:[0,0,1]
	v_pk_mul_f32 v[22:23], v[54:55], v[58:59]
	s_nop 0
	v_pk_fma_f32 v[62:63], v[32:33], v[52:53], v[22:23]
	v_mov_b32_e32 v22, v180
	s_waitcnt vmcnt(12)
	v_mov_b32_e32 v23, v170
	v_mov_b32_e32 v170, v181
	v_pk_mul_f32 v[64:65], v[176:177], v[170:171]
	v_pk_mul_f32 v[66:67], v[176:177], v[22:23]
	v_pk_fma_f32 v[64:65], v[56:57], v[22:23], v[64:65] neg_lo:[0,0,1] neg_hi:[0,0,1]
	v_pk_fma_f32 v[56:57], v[56:57], v[170:171], v[66:67]
	s_nop 0
	v_pk_mul_f32 v[68:69], v[30:31], v[56:57]
	v_pk_mul_f32 v[66:67], v[24:25], v[56:57]
	v_pk_fma_f32 v[68:69], v[24:25], v[64:65], v[68:69]
	v_pk_fma_f32 v[66:67], v[30:31], v[64:65], v[66:67] neg_lo:[0,0,1] neg_hi:[0,0,1]
	v_cvt_pk_bf16_f32 v61, v61, v63
	v_cvt_pk_bf16_f32 v63, v67, v69
	v_cvt_pk_bf16_f32 v60, v60, v62
	v_cvt_pk_bf16_f32 v62, v66, v68
	s_nop 1
	v_mfma_f32_16x16x32_bf16 v[46:49], v[14:17], v[60:63], v[46:49]
	v_mul_f32_e64 v60, v172, v58
	v_mul_f32_e64 v61, v173, v59
	v_pk_mul_f32 v[58:59], v[50:51], v[58:59]
	v_pk_fma_f32 v[60:61], v[50:51], v[52:53], v[60:61] neg_lo:[0,0,1] neg_hi:[0,0,1]
	v_pk_fma_f32 v[52:53], v[172:173], v[52:53], v[58:59]
	s_nop 0
	v_pk_mul_f32 v[66:67], v[172:173], v[52:53]
	v_pk_mul_f32 v[58:59], v[32:33], v[52:53]
	v_pk_fma_f32 v[66:67], v[50:51], v[60:61], v[66:67] neg_lo:[0,0,1] neg_hi:[0,0,1]
	v_pk_mul_f32 v[50:51], v[50:51], v[52:53]
	v_pk_mul_f32 v[62:63], v[54:55], v[52:53]
	v_pk_fma_f32 v[50:51], v[172:173], v[60:61], v[50:51]
	v_pk_fma_f32 v[58:59], v[54:55], v[60:61], v[58:59] neg_lo:[0,0,1] neg_hi:[0,0,1]
	v_pk_mul_f32 v[52:53], v[32:33], v[50:51]
	v_pk_fma_f32 v[62:63], v[32:33], v[60:61], v[62:63]
	v_pk_fma_f32 v[60:61], v[54:55], v[66:67], v[52:53] neg_lo:[0,0,1] neg_hi:[0,0,1]
	v_pk_mul_f32 v[50:51], v[54:55], v[50:51]
	v_pk_mul_f32 v[52:53], v[22:23], v[56:57]
	v_pk_fma_f32 v[32:33], v[32:33], v[66:67], v[50:51]
	v_pk_mul_f32 v[50:51], v[170:171], v[56:57]
	v_pk_fma_f32 v[52:53], v[170:171], v[64:65], v[52:53]
	v_pk_fma_f32 v[50:51], v[22:23], v[64:65], v[50:51] neg_lo:[0,0,1] neg_hi:[0,0,1]
	v_pk_mul_f32 v[56:57], v[30:31], v[52:53]
	v_pk_mul_f32 v[64:65], v[170:171], v[52:53]
	v_pk_mul_f32 v[54:55], v[24:25], v[52:53]
	v_pk_fma_f32 v[56:57], v[24:25], v[50:51], v[56:57]
	v_pk_fma_f32 v[64:65], v[22:23], v[50:51], v[64:65] neg_lo:[0,0,1] neg_hi:[0,0,1]
	v_pk_mul_f32 v[22:23], v[22:23], v[52:53]
	v_pk_fma_f32 v[54:55], v[30:31], v[50:51], v[54:55] neg_lo:[0,0,1] neg_hi:[0,0,1]
	v_pk_fma_f32 v[22:23], v[170:171], v[50:51], v[22:23]
	v_cvt_pk_bf16_f32 v53, v55, v57
	v_cvt_pk_bf16_f32 v52, v54, v56
	v_cvt_pk_bf16_f32 v51, v59, v63
	v_cvt_pk_bf16_f32 v50, v58, v62
	s_nop 1
	v_mfma_f32_16x16x32_bf16 v[42:45], v[14:17], v[50:53], v[42:45]
	v_mul_f32_e64 v50, v24, v22
	v_mul_f32_e64 v51, v25, v23
	v_pk_mul_f32 v[22:23], v[30:31], v[22:23]
	v_pk_fma_f32 v[50:51], v[30:31], v[64:65], v[50:51] neg_lo:[0,0,1] neg_hi:[0,0,1]
	v_pk_fma_f32 v[22:23], v[24:25], v[64:65], v[22:23]
	s_nop 0
	v_cvt_pk_bf16_f32 v25, v51, v23
	v_cvt_pk_bf16_f32 v23, v61, v33
	v_cvt_pk_bf16_f32 v24, v50, v22
	v_cvt_pk_bf16_f32 v22, v60, v32
	s_waitcnt vmcnt(7)
	v_mov_b32_e32 v50, v26
	v_mov_b32_e32 v51, v28
	v_mfma_f32_16x16x32_bf16 v[34:37], v[14:17], v[22:25], v[34:37]
	s_waitcnt vmcnt(6)
	v_mov_b32_e32 v23, v164
	v_mov_b32_e32 v164, v163
	v_mov_b32_e32 v28, v27
	s_waitcnt vmcnt(4)
	v_mov_b32_e32 v25, v174
	v_mov_b32_e32 v26, v18
	v_mov_b32_e32 v27, v20
	s_waitcnt vmcnt(3)
	v_mov_b32_e32 v174, v169
	v_mov_b32_e32 v22, v162
	v_pk_mul_f32 v[16:17], v[164:165], v[50:51]
	v_mov_b32_e32 v24, v168
	v_mov_b32_e32 v20, v19
	v_pk_mul_f32 v[30:31], v[174:175], v[26:27]
	v_pk_mul_f32 v[14:15], v[164:165], v[28:29]
	v_pk_fma_f32 v[16:17], v[22:23], v[28:29], v[16:17]
	v_pk_mul_f32 v[18:19], v[174:175], v[20:21]
	v_pk_fma_f32 v[30:31], v[24:25], v[20:21], v[30:31]
	v_pk_fma_f32 v[14:15], v[22:23], v[50:51], v[14:15] neg_lo:[0,0,1] neg_hi:[0,0,1]
	v_pk_fma_f32 v[18:19], v[24:25], v[26:27], v[18:19] neg_lo:[0,0,1] neg_hi:[0,0,1]
	v_cvt_pk_bf16_f32 v15, v15, v17
	v_cvt_pk_bf16_f32 v17, v19, v31
	v_cvt_pk_bf16_f32 v14, v14, v16
	v_cvt_pk_bf16_f32 v16, v18, v30
	v_mov_b32_e32 v19, v158
	v_mov_b32_e32 v158, v161
	v_mfma_f32_16x16x32_bf16 v[30:33], v[10:13], v[14:17], v[38:41]
	v_mov_b32_e32 v18, v160
	v_pk_mul_f32 v[14:15], v[164:165], v[158:159]
	s_waitcnt vmcnt(1)
	v_mov_b32_e32 v53, v188
	v_pk_fma_f32 v[38:39], v[22:23], v[18:19], v[14:15] neg_lo:[0,0,1] neg_hi:[0,0,1]
	v_pk_mul_f32 v[14:15], v[164:165], v[18:19]
	v_mov_b32_e32 v188, v167
	v_pk_fma_f32 v[40:41], v[22:23], v[158:159], v[14:15]
	v_mov_b32_e32 v52, v166
	v_pk_mul_f32 v[22:23], v[174:175], v[188:189]
	v_pk_mul_f32 v[16:17], v[50:51], v[40:41]
	v_pk_fma_f32 v[54:55], v[24:25], v[52:53], v[22:23] neg_lo:[0,0,1] neg_hi:[0,0,1]
	v_pk_mul_f32 v[22:23], v[174:175], v[52:53]
	v_pk_mul_f32 v[14:15], v[28:29], v[40:41]
	v_pk_fma_f32 v[56:57], v[24:25], v[188:189], v[22:23]
	v_pk_fma_f32 v[16:17], v[28:29], v[38:39], v[16:17]
	v_pk_mul_f32 v[24:25], v[26:27], v[56:57]
	v_pk_mul_f32 v[22:23], v[20:21], v[56:57]
	v_pk_fma_f32 v[24:25], v[20:21], v[54:55], v[24:25]
	v_pk_fma_f32 v[14:15], v[50:51], v[38:39], v[14:15] neg_lo:[0,0,1] neg_hi:[0,0,1]
	v_pk_fma_f32 v[22:23], v[26:27], v[54:55], v[22:23] neg_lo:[0,0,1] neg_hi:[0,0,1]
	v_cvt_pk_bf16_f32 v15, v15, v17
	v_cvt_pk_bf16_f32 v17, v23, v25
	v_cvt_pk_bf16_f32 v14, v14, v16
	v_cvt_pk_bf16_f32 v16, v22, v24
	s_nop 1
	v_mfma_f32_16x16x32_bf16 v[22:25], v[10:13], v[14:17], v[46:49]
	v_mul_f32_e64 v16, v18, v40
	v_mul_f32_e64 v17, v19, v41
	v_pk_mul_f32 v[14:15], v[158:159], v[40:41]
	v_pk_fma_f32 v[16:17], v[158:159], v[38:39], v[16:17]
	v_pk_fma_f32 v[14:15], v[18:19], v[38:39], v[14:15] neg_lo:[0,0,1] neg_hi:[0,0,1]
	v_pk_mul_f32 v[38:39], v[28:29], v[16:17]
	v_pk_mul_f32 v[40:41], v[50:51], v[16:17]
	v_pk_mul_f32 v[46:47], v[158:159], v[16:17]
	v_pk_mul_f32 v[16:17], v[18:19], v[16:17]
	v_pk_fma_f32 v[38:39], v[50:51], v[14:15], v[38:39] neg_lo:[0,0,1] neg_hi:[0,0,1]
	v_pk_fma_f32 v[40:41], v[28:29], v[14:15], v[40:41]
	v_pk_fma_f32 v[46:47], v[18:19], v[14:15], v[46:47] neg_lo:[0,0,1] neg_hi:[0,0,1]
	v_pk_fma_f32 v[14:15], v[158:159], v[14:15], v[16:17]
	s_nop 0
	v_pk_mul_f32 v[16:17], v[28:29], v[14:15]
	v_pk_mul_f32 v[14:15], v[50:51], v[14:15]
	v_pk_fma_f32 v[18:19], v[50:51], v[46:47], v[16:17] neg_lo:[0,0,1] neg_hi:[0,0,1]
	v_pk_mul_f32 v[16:17], v[52:53], v[56:57]
	v_pk_fma_f32 v[28:29], v[28:29], v[46:47], v[14:15]
	v_pk_mul_f32 v[14:15], v[188:189], v[56:57]
	v_pk_fma_f32 v[16:17], v[188:189], v[54:55], v[16:17]
	v_pk_fma_f32 v[14:15], v[52:53], v[54:55], v[14:15] neg_lo:[0,0,1] neg_hi:[0,0,1]
	v_pk_mul_f32 v[48:49], v[26:27], v[16:17]
	v_pk_mul_f32 v[46:47], v[20:21], v[16:17]
	v_pk_fma_f32 v[48:49], v[20:21], v[14:15], v[48:49]
	v_pk_mul_f32 v[50:51], v[188:189], v[16:17]
	v_pk_mul_f32 v[16:17], v[52:53], v[16:17]
	v_pk_fma_f32 v[46:47], v[26:27], v[14:15], v[46:47] neg_lo:[0,0,1] neg_hi:[0,0,1]
	v_pk_fma_f32 v[50:51], v[52:53], v[14:15], v[50:51] neg_lo:[0,0,1] neg_hi:[0,0,1]
	v_pk_fma_f32 v[52:53], v[188:189], v[14:15], v[16:17]
	v_cvt_pk_bf16_f32 v17, v47, v49
	v_cvt_pk_bf16_f32 v16, v46, v48
	v_cvt_pk_bf16_f32 v15, v39, v41
	v_cvt_pk_bf16_f32 v14, v38, v40
	v_pk_mul_f32 v[38:39], v[20:21], v[52:53]
	s_nop 0
	v_pk_fma_f32 v[38:39], v[26:27], v[50:51], v[38:39] neg_lo:[0,0,1] neg_hi:[0,0,1]
	v_pk_mul_f32 v[26:27], v[26:27], v[52:53]
	s_nop 0
	v_pk_fma_f32 v[20:21], v[20:21], v[50:51], v[26:27]
	v_cvt_pk_bf16_f32 v19, v19, v29
	v_cvt_pk_bf16_f32 v18, v18, v28
	v_cvt_pk_bf16_f32 v21, v39, v21
	v_cvt_pk_bf16_f32 v20, v38, v20
	v_mfma_f32_16x16x32_bf16 v[14:17], v[10:13], v[14:17], v[42:45]
	v_mov_b32_e32 v29, v32
	v_mov_b32_e32 v32, v31
	v_mov_b32_e32 v28, v30
	v_mfma_f32_16x16x32_bf16 v[10:13], v[10:13], v[18:21], v[34:37]
	s_waitcnt vmcnt(0)
	v_mov_b32_e32 v19, v8
	v_mov_b32_e32 v8, v7
	v_mov_b32_e32 v18, v6
	v_add_u32_e32 v34, s22, v242
	ds_read_b64 v[20:21], v34
	v_add_u32_e32 v242, 32, v242
	s_waitcnt lgkmcnt(0)
	v_lshlrev_b32_e32 v27, 16, v21
	v_lshlrev_b32_e32 v26, 16, v20
	v_and_b32_e32 v21, 0xffff0000, v21
	v_and_b32_e32 v20, 0xffff0000, v20
	v_pk_fma_f32 v[20:21], v[8:9], v[20:21], v[32:33]
	v_pk_fma_f32 v[26:27], v[18:19], v[26:27], v[28:29]
	v_mul_f32_e32 v7, 0x3d372713, v20
	v_mul_f32_e32 v7, v20, v7
	v_fma_f32 v7, v20, v7, v20
	v_mul_f32_e32 v7, 0x3f4c422a, v7
	v_mul_f32_e32 v7, -2.0, v7
	v_mul_f32_e32 v7, 0x3fb8aa3b, v7
	v_exp_f32_e32 v7, v7
	v_mul_f32_e32 v6, 0x3d372713, v26
	v_mul_f32_e32 v6, v26, v6
	v_fma_f32 v6, v26, v6, v26
	v_add_f32_e32 v7, 1.0, v7
	v_rcp_f32_e32 v28, v7
	v_mul_f32_e32 v7, 0x3d372713, v27
	v_mul_f32_e32 v7, v27, v7
	v_fma_f32 v7, v27, v7, v27
	v_mul_f32_e32 v6, 0x3f4c422a, v6
	v_mul_f32_e32 v7, 0x3f4c422a, v7
	v_mul_f32_e32 v6, -2.0, v6
	v_mul_f32_e32 v7, -2.0, v7
	v_mul_f32_e32 v6, 0x3fb8aa3b, v6
	v_mul_f32_e32 v7, 0x3fb8aa3b, v7
	v_exp_f32_e32 v6, v6
	v_exp_f32_e32 v7, v7
	v_add_f32_e32 v6, 1.0, v6
	v_add_f32_e32 v7, 1.0, v7
	v_rcp_f32_e32 v6, v6
	v_rcp_f32_e32 v7, v7
	s_nop 0
	v_pk_mul_f32 v[6:7], v[26:27], v[6:7]
	v_mul_f32_e32 v26, 0x3d372713, v21
	v_mul_f32_e32 v26, v21, v26
	v_fma_f32 v26, v21, v26, v21
	v_mul_f32_e32 v26, 0x3f4c422a, v26
	v_mul_f32_e32 v26, -2.0, v26
	v_mul_f32_e32 v26, 0x3fb8aa3b, v26
	v_exp_f32_e32 v26, v26
	s_nop 0
	v_add_f32_e32 v26, 1.0, v26
	v_rcp_f32_e32 v29, v26
	s_nop 0
	v_pk_mul_f32 v[20:21], v[20:21], v[28:29]
	s_nop 0
	v_cvt_pk_bf16_f32 v6, v6, v20
	v_cvt_pk_bf16_f32 v7, v7, v21
	ds_write_b64 v34, v[6:7]
	v_add_u32_e32 v28, s22, v241
	ds_read_b64 v[6:7], v28 offset:33280
	v_mov_b32_e32 v27, v24
	v_mov_b32_e32 v24, v23
	v_mov_b32_e32 v26, v22
	v_add_u32_e32 v241, 32, v241
	s_waitcnt lgkmcnt(0)
	v_lshlrev_b32_e32 v21, 16, v7
	v_lshlrev_b32_e32 v20, 16, v6
	v_and_b32_e32 v7, 0xffff0000, v7
	v_and_b32_e32 v6, 0xffff0000, v6
	v_pk_fma_f32 v[6:7], v[8:9], v[6:7], v[24:25]
	v_pk_fma_f32 v[20:21], v[18:19], v[20:21], v[26:27]
	v_mul_f32_e32 v23, 0x3d372713, v6
	v_mul_f32_e32 v23, v6, v23
	v_fma_f32 v23, v6, v23, v6
	v_mul_f32_e32 v23, 0x3f4c422a, v23
	v_mul_f32_e32 v23, -2.0, v23
	v_mul_f32_e32 v23, 0x3fb8aa3b, v23
	v_exp_f32_e32 v23, v23
	v_mul_f32_e32 v22, 0x3d372713, v20
	v_mul_f32_e32 v22, v20, v22
	v_fma_f32 v22, v20, v22, v20
	v_add_f32_e32 v23, 1.0, v23
	v_rcp_f32_e32 v24, v23
	v_mul_f32_e32 v23, 0x3d372713, v21
	v_mul_f32_e32 v23, v21, v23
	v_fma_f32 v23, v21, v23, v21
	v_mul_f32_e32 v22, 0x3f4c422a, v22
	v_mul_f32_e32 v23, 0x3f4c422a, v23
	v_mul_f32_e32 v22, -2.0, v22
	v_mul_f32_e32 v23, -2.0, v23
	v_mul_f32_e32 v22, 0x3fb8aa3b, v22
	v_mul_f32_e32 v23, 0x3fb8aa3b, v23
	v_exp_f32_e32 v22, v22
	v_exp_f32_e32 v23, v23
	v_add_f32_e32 v22, 1.0, v22
	v_add_f32_e32 v23, 1.0, v23
	v_rcp_f32_e32 v22, v22
	v_rcp_f32_e32 v23, v23
	s_nop 0
	v_pk_mul_f32 v[20:21], v[20:21], v[22:23]
	v_mul_f32_e32 v22, 0x3d372713, v7
	v_mul_f32_e32 v22, v7, v22
	v_fma_f32 v22, v7, v22, v7
	v_mul_f32_e32 v22, 0x3f4c422a, v22
	v_mul_f32_e32 v22, -2.0, v22
	v_mul_f32_e32 v22, 0x3fb8aa3b, v22
	v_exp_f32_e32 v22, v22
	s_nop 0
	v_add_f32_e32 v22, 1.0, v22
	v_rcp_f32_e32 v25, v22
	s_nop 0
	v_pk_mul_f32 v[6:7], v[6:7], v[24:25]
	s_nop 0
	v_cvt_pk_bf16_f32 v6, v20, v6
	v_cvt_pk_bf16_f32 v7, v21, v7
	ds_write_b64 v28, v[6:7] offset:33280
	ds_read_b64 v[6:7], v28 offset:49920
	v_mov_b32_e32 v23, v16
	v_mov_b32_e32 v16, v15
	v_mov_b32_e32 v22, v14
	s_waitcnt lgkmcnt(0)
	v_lshlrev_b32_e32 v21, 16, v7
	v_lshlrev_b32_e32 v20, 16, v6
	v_and_b32_e32 v7, 0xffff0000, v7
	v_and_b32_e32 v6, 0xffff0000, v6
	v_pk_fma_f32 v[6:7], v[8:9], v[6:7], v[16:17]
	v_pk_fma_f32 v[20:21], v[18:19], v[20:21], v[22:23]
	v_mul_f32_e32 v15, 0x3d372713, v6
	v_mul_f32_e32 v15, v6, v15
	v_fma_f32 v15, v6, v15, v6
	v_mul_f32_e32 v15, 0x3f4c422a, v15
	v_mul_f32_e32 v15, -2.0, v15
	v_mul_f32_e32 v15, 0x3fb8aa3b, v15
	v_exp_f32_e32 v15, v15
	v_mul_f32_e32 v14, 0x3d372713, v20
	v_mul_f32_e32 v14, v20, v14
	v_mul_f32_e32 v17, 0x3d372713, v7
	v_add_f32_e32 v15, 1.0, v15
	v_rcp_f32_e32 v16, v15
	v_mul_f32_e32 v15, 0x3d372713, v21
	v_mul_f32_e32 v15, v21, v15
	v_fma_f32 v14, v20, v14, v20
	v_fma_f32 v15, v21, v15, v21
	v_mul_f32_e32 v17, v7, v17
	v_mul_f32_e32 v14, 0x3f4c422a, v14
	v_mul_f32_e32 v15, 0x3f4c422a, v15
	v_fma_f32 v17, v7, v17, v7
	v_mul_f32_e32 v14, -2.0, v14
	v_mul_f32_e32 v15, -2.0, v15
	v_mul_f32_e32 v17, 0x3f4c422a, v17
	v_mul_f32_e32 v14, 0x3fb8aa3b, v14
	v_mul_f32_e32 v15, 0x3fb8aa3b, v15
	v_mul_f32_e32 v17, -2.0, v17
	v_exp_f32_e32 v14, v14
	v_exp_f32_e32 v15, v15
	v_mul_f32_e32 v17, 0x3fb8aa3b, v17
	v_exp_f32_e32 v17, v17
	v_add_f32_e32 v14, 1.0, v14
	v_add_f32_e32 v15, 1.0, v15
	v_rcp_f32_e32 v14, v14
	v_rcp_f32_e32 v15, v15
	v_add_f32_e32 v17, 1.0, v17
	v_rcp_f32_e32 v17, v17
	v_pk_mul_f32 v[14:15], v[20:21], v[14:15]
	v_add_u32_e32 v20, 0x10400, v28
	v_pk_mul_f32 v[6:7], v[6:7], v[16:17]
	s_nop 0
	v_cvt_pk_bf16_f32 v7, v15, v7
	v_cvt_pk_bf16_f32 v6, v14, v6
	ds_write_b64 v28, v[6:7] offset:49920
	ds_read_b64 v[6:7], v20
	v_mov_b32_e32 v16, v10
	v_mov_b32_e32 v17, v12
	v_mov_b32_e32 v12, v11
	s_waitcnt lgkmcnt(0)
	v_lshlrev_b32_e32 v15, 16, v7
	v_lshlrev_b32_e32 v14, 16, v6
	v_pk_fma_f32 v[14:15], v[18:19], v[14:15], v[16:17]
	v_and_b32_e32 v7, 0xffff0000, v7
	v_and_b32_e32 v6, 0xffff0000, v6
	v_pk_fma_f32 v[6:7], v[8:9], v[6:7], v[12:13]
	v_mul_f32_e32 v9, 0x3d372713, v15
	v_mul_f32_e32 v9, v15, v9
	v_fma_f32 v9, v15, v9, v15
	v_mul_f32_e32 v9, 0x3f4c422a, v9
	v_mul_f32_e32 v9, -2.0, v9
	v_mul_f32_e32 v9, 0x3fb8aa3b, v9
	v_exp_f32_e32 v9, v9
	v_mul_f32_e32 v10, 0x3d372713, v14
	v_mul_f32_e32 v10, v14, v10
	v_mul_f32_e32 v8, 0x3d372713, v6
	v_add_f32_e32 v9, 1.0, v9
	v_rcp_f32_e32 v11, v9
	v_mul_f32_e32 v9, 0x3d372713, v7
	v_fma_f32 v10, v14, v10, v14
	v_mul_f32_e32 v8, v6, v8
	v_mul_f32_e32 v9, v7, v9
	v_mul_f32_e32 v10, 0x3f4c422a, v10
	v_fma_f32 v8, v6, v8, v6
	v_fma_f32 v9, v7, v9, v7
	v_mul_f32_e32 v10, -2.0, v10
	v_mul_f32_e32 v8, 0x3f4c422a, v8
	v_mul_f32_e32 v9, 0x3f4c422a, v9
	v_mul_f32_e32 v10, 0x3fb8aa3b, v10
	v_mul_f32_e32 v8, -2.0, v8
	v_mul_f32_e32 v9, -2.0, v9
	v_exp_f32_e32 v10, v10
	v_mul_f32_e32 v8, 0x3fb8aa3b, v8
	v_mul_f32_e32 v9, 0x3fb8aa3b, v9
	v_exp_f32_e32 v8, v8
	v_exp_f32_e32 v9, v9
	v_add_f32_e32 v10, 1.0, v10
	v_rcp_f32_e32 v10, v10
	v_add_f32_e32 v8, 1.0, v8
	v_add_f32_e32 v9, 1.0, v9
	v_rcp_f32_e32 v8, v8
	v_rcp_f32_e32 v9, v9
	v_pk_mul_f32 v[10:11], v[14:15], v[10:11]
	v_pk_mul_f32 v[6:7], v[6:7], v[8:9]
	s_nop 0
	v_cvt_pk_bf16_f32 v7, v11, v7
	v_cvt_pk_bf16_f32 v6, v10, v6
	ds_write_b64 v20, v[6:7]
	s_cbranch_scc0 .LBB0_464
	s_and_b32 s0, s20, 0xffffffc0
	v_or_b32_e32 v6, s0, v1
	v_ashrrev_i32_e32 v7, 31, v6
	v_readlane_b32 s4, v254, 8
	v_lshlrev_b64 v[10:11], 10, v[6:7]
	v_readlane_b32 s5, v254, 9
	s_ashr_i32 s1, s0, 31
	v_readlane_b32 s6, v254, 10
	v_lshl_add_u64 v[6:7], s[4:5], 0, v[10:11]
	s_nop 1
	s_mov_b64 s[36:37], s[4:5]
	s_add_u32 s38, s4, 0x4000
	s_addc_u32 s39, s5, 0
	s_add_u32 s40, s4, 0x8000
	s_addc_u32 s41, s5, 0
	s_add_u32 s44, s4, 0xc000
	s_addc_u32 s45, s5, 0
	s_lshl_b64 s[4:5], s[0:1], 2
	s_add_u32 s4, s6, s4
	v_readlane_b32 s6, v254, 11
	s_addc_u32 s5, s6, s5
	v_readlane_b32 s6, v251, 55
	v_lshlrev_b32_e32 v12, 1, v238
	v_add_u32_e32 v239, v10, v12
	v_mov_b32_e32 v13, v139
	v_readlane_b32 s7, v251, 56
	v_lshl_add_u64 v[136:137], v[6:7], 0, v[12:13]
	v_or_b32_e32 v22, s88, v1
	v_mov_b64_e32 v[6:7], s[6:7]
	s_movk_i32 s10, 0x2800
	v_mad_i64_i32 v[134:135], s[6:7], v22, s10, v[6:7]
	s_lshl_b64 s[6:7], s[0:1], 1
	s_nop 0
	v_lshl_add_u64 v[8:9], v[134:135], 0, s[6:7]
	v_lshlrev_b32_e32 v14, 1, v146
	v_mov_b32_e32 v15, v139
	v_lshl_add_u64 v[16:17], v[8:9], 0, v[14:15]
	v_or_b32_e32 v8, 16, v22
	v_mad_i64_i32 v[8:9], s[8:9], v8, s10, v[6:7]
	v_lshl_add_u64 v[8:9], v[8:9], 0, s[6:7]
	v_lshl_add_u64 v[18:19], v[8:9], 0, v[14:15]
	v_or_b32_e32 v8, 32, v22
	v_mad_i64_i32 v[8:9], s[8:9], v8, s10, v[6:7]
	v_lshl_add_u64 v[8:9], v[8:9], 0, s[6:7]
	v_lshl_add_u64 v[20:21], v[8:9], 0, v[14:15]
	v_or_b32_e32 v8, 48, v22
	v_mad_i64_i32 v[6:7], s[8:9], v8, s10, v[6:7]
	v_lshl_add_u64 v[6:7], v[6:7], 0, s[6:7]
	v_lshl_add_u64 v[14:15], v[6:7], 0, v[14:15]
	v_add_co_u32_e32 v6, vcc, s69, v136
	v_lshlrev_b32_e32 v13, 2, v146
	s_nop 0
	v_addc_co_u32_e32 v7, vcc, 0, v137, vcc
	v_add_co_u32_e32 v8, vcc, s19, v136
	s_nop 0
	s_nop 0
	v_addc_co_u32_e32 v9, vcc, 0, v137, vcc
	s_nop 0
	s_nop 0
	s_nop 0
	s_nop 0
	v_add_co_u32_e32 v6, vcc, s27, v136
	v_add_u32_e32 v150, 0, v237
	s_nop 0
	v_addc_co_u32_e32 v7, vcc, 0, v137, vcc
	s_nop 0
	s_nop 0
	s_nop 0
	s_nop 0
	v_lshlrev_b32_e32 v220, 2, v146
	s_mov_b64 s[46:47], s[4:5]
	global_load_dwordx4 v[74:77], v239, s[36:37] offset:0
	global_load_dwordx4 v[140:143], v239, s[36:37] offset:64
	global_load_dwordx4 v[96:99], v239, s[38:39] offset:0
	global_load_dwordx4 v[152:155], v239, s[38:39] offset:64
	global_load_dwordx4 v[92:95], v239, s[40:41] offset:0
	global_load_dwordx4 v[156:159], v239, s[40:41] offset:64
	global_load_dwordx4 v[88:91], v239, s[44:45] offset:0
	global_load_dwordx4 v[160:163], v239, s[44:45] offset:64
	global_load_dwordx4 v[180:183], v239, s[36:37] offset:128
	global_load_dwordx4 v[196:199], v239, s[36:37] offset:192
	global_load_dwordx4 v[184:187], v239, s[38:39] offset:128
	global_load_dwordx4 v[200:203], v239, s[38:39] offset:192
	global_load_dwordx4 v[188:191], v239, s[40:41] offset:128
	global_load_dwordx4 v[204:207], v239, s[40:41] offset:192
	global_load_dwordx4 v[192:195], v239, s[44:45] offset:128
	global_load_dwordx4 v[208:211], v239, s[44:45] offset:192
	global_load_dwordx4 v[212:215], v239, s[36:37] offset:256
	global_load_dwordx4 v[66:69], v239, s[36:37] offset:320
	global_load_dwordx4 v[216:219], v239, s[38:39] offset:256
	global_load_dwordx4 v[46:49], v239, s[38:39] offset:320
	global_load_dwordx4 v[240:243], v239, s[40:41] offset:256
	global_load_dwordx4 v[26:29], v239, s[40:41] offset:320
	global_load_dwordx4 v[244:247], v239, s[44:45] offset:256
	global_load_dwordx4 v[6:9], v239, s[44:45] offset:320
	global_load_dwordx2 v[78:79], v[16:17], off offset:2560
	global_load_dwordx2 v[126:127], v[16:17], off offset:2592
	global_load_dwordx2 v[118:119], v[16:17], off offset:2624
	global_load_dwordx2 v[110:111], v[16:17], off offset:2656
	global_load_dwordx2 v[132:133], v[18:19], off offset:2560
	global_load_dwordx2 v[124:125], v[18:19], off offset:2592
	global_load_dwordx2 v[116:117], v[18:19], off offset:2624
	global_load_dwordx2 v[108:109], v[18:19], off offset:2656
	global_load_dwordx2 v[130:131], v[20:21], off offset:2560
	global_load_dwordx2 v[122:123], v[20:21], off offset:2592
	global_load_dwordx2 v[114:115], v[20:21], off offset:2624
	global_load_dwordx2 v[106:107], v[20:21], off offset:2656
	global_load_dwordx2 v[128:129], v[14:15], off offset:2560
	global_load_dwordx2 v[120:121], v[14:15], off offset:2592
	global_load_dwordx2 v[112:113], v[14:15], off offset:2624
	global_load_dwordx2 v[104:105], v[14:15], off offset:2656
	v_readlane_b32 s4, v254, 61
	v_or_b32_e32 v10, v10, v138
	v_readlane_b32 s5, v254, 62
	v_mov_b32_e32 v30, 0
	v_add_u32_e32 v151, v150, v12
	v_lshl_add_u64 v[148:149], s[4:5], 0, v[10:11]
	s_mov_b64 s[22:23], 0
	s_mov_b32 s1, 64
	v_mov_b32_e32 v31, v30
	v_mov_b32_e32 v32, v30
	v_mov_b32_e32 v33, v30
	v_mov_b32_e32 v34, v30
	v_mov_b32_e32 v35, v30
	v_mov_b32_e32 v36, v30
	v_mov_b32_e32 v37, v30
	v_mov_b32_e32 v38, v30
	v_mov_b32_e32 v39, v30
	v_mov_b32_e32 v40, v30
	v_mov_b32_e32 v41, v30
	v_mov_b32_e32 v42, v30
	v_mov_b32_e32 v43, v30
	v_mov_b32_e32 v44, v30
	v_mov_b32_e32 v45, v30
	v_mov_b32_e32 v50, v30
	v_mov_b32_e32 v51, v30
	v_mov_b32_e32 v52, v30
	v_mov_b32_e32 v53, v30
	v_mov_b32_e32 v54, v30
	v_mov_b32_e32 v55, v30
	v_mov_b32_e32 v56, v30
	v_mov_b32_e32 v57, v30
	v_mov_b32_e32 v58, v30
	v_mov_b32_e32 v59, v30
	v_mov_b32_e32 v60, v30
	v_mov_b32_e32 v61, v30
	v_mov_b32_e32 v62, v30
	v_mov_b32_e32 v63, v30
	v_mov_b32_e32 v64, v30
	v_mov_b32_e32 v65, v30
	v_mov_b32_e32 v70, v30
	v_mov_b32_e32 v71, v30
	v_mov_b32_e32 v72, v30
	v_mov_b32_e32 v73, v30
	v_mov_b32_e32 v84, v30
	v_mov_b32_e32 v85, v30
	v_mov_b32_e32 v86, v30
	v_mov_b32_e32 v87, v30
	v_mov_b32_e32 v80, v30
	v_mov_b32_e32 v81, v30
	v_mov_b32_e32 v82, v30
	v_mov_b32_e32 v83, v30
	v_mov_b32_e32 v100, v30
	v_mov_b32_e32 v101, v30
	v_mov_b32_e32 v102, v30
	v_mov_b32_e32 v103, v30
	v_mov_b32_e32 v22, v30
	v_mov_b32_e32 v23, v30
	v_mov_b32_e32 v24, v30
	v_mov_b32_e32 v25, v30
	v_mov_b32_e32 v18, v30
	v_mov_b32_e32 v19, v30
	v_mov_b32_e32 v20, v30
	v_mov_b32_e32 v21, v30
	v_mov_b32_e32 v14, v30
	v_mov_b32_e32 v15, v30
	v_mov_b32_e32 v16, v30
	v_mov_b32_e32 v17, v30
	v_mov_b32_e32 v10, v30
	v_mov_b32_e32 v11, v30
	v_mov_b32_e32 v12, v30
	v_mov_b32_e32 v13, v30
	s_waitcnt lgkmcnt(0)
	s_barrier
.LBB0_466:
	v_add_u32_e32 v138, 0x10400, v151
	ds_read_b128 v[164:167], v151 offset:16640
	ds_read_b128 v[172:175], v151 offset:33280
	ds_read_b128 v[168:171], v151 offset:49920
	ds_read_b128 v[176:179], v138 offset:0
	s_waitcnt vmcnt(33)
	s_waitcnt lgkmcnt(3)
	v_mfma_f32_16x16x32_bf16 v[100:103], v[74:77], v[164:167], v[100:103]
	v_mfma_f32_16x16x32_bf16 v[62:65], v[96:99], v[164:167], v[62:65]
	v_mfma_f32_16x16x32_bf16 v[42:45], v[92:95], v[164:167], v[42:45]
	v_mfma_f32_16x16x32_bf16 v[22:25], v[88:91], v[164:167], v[22:25]
	ds_read_b128 v[164:167], v151 offset:16704
	s_waitcnt lgkmcnt(3)
	v_mfma_f32_16x16x32_bf16 v[80:83], v[74:77], v[172:175], v[80:83]
	v_mfma_f32_16x16x32_bf16 v[58:61], v[96:99], v[172:175], v[58:61]
	v_mfma_f32_16x16x32_bf16 v[38:41], v[92:95], v[172:175], v[38:41]
	v_mfma_f32_16x16x32_bf16 v[18:21], v[88:91], v[172:175], v[18:21]
	ds_read_b128 v[172:175], v151 offset:33344
	s_waitcnt lgkmcnt(3)
	v_mfma_f32_16x16x32_bf16 v[84:87], v[74:77], v[168:171], v[84:87]
	v_mfma_f32_16x16x32_bf16 v[54:57], v[96:99], v[168:171], v[54:57]
	v_mfma_f32_16x16x32_bf16 v[34:37], v[92:95], v[168:171], v[34:37]
	v_mfma_f32_16x16x32_bf16 v[14:17], v[88:91], v[168:171], v[14:17]
	ds_read_b128 v[168:171], v151 offset:49984
	s_waitcnt lgkmcnt(3)
	v_mfma_f32_16x16x32_bf16 v[70:73], v[74:77], v[176:179], v[70:73]
	v_mfma_f32_16x16x32_bf16 v[50:53], v[96:99], v[176:179], v[50:53]
	v_mfma_f32_16x16x32_bf16 v[30:33], v[92:95], v[176:179], v[30:33]
	v_mfma_f32_16x16x32_bf16 v[10:13], v[88:91], v[176:179], v[10:13]
	ds_read_b128 v[176:179], v138 offset:64
	s_waitcnt vmcnt(32)
	s_waitcnt lgkmcnt(3)
	v_mfma_f32_16x16x32_bf16 v[100:103], v[140:143], v[164:167], v[100:103]
	v_mfma_f32_16x16x32_bf16 v[62:65], v[152:155], v[164:167], v[62:65]
	v_mfma_f32_16x16x32_bf16 v[42:45], v[156:159], v[164:167], v[42:45]
	v_mfma_f32_16x16x32_bf16 v[22:25], v[160:163], v[164:167], v[22:25]
	ds_read_b128 v[164:167], v151 offset:16768
	s_waitcnt lgkmcnt(3)
	v_mfma_f32_16x16x32_bf16 v[80:83], v[140:143], v[172:175], v[80:83]
	v_mfma_f32_16x16x32_bf16 v[58:61], v[152:155], v[172:175], v[58:61]
	v_mfma_f32_16x16x32_bf16 v[38:41], v[156:159], v[172:175], v[38:41]
	v_mfma_f32_16x16x32_bf16 v[18:21], v[160:163], v[172:175], v[18:21]
	ds_read_b128 v[172:175], v151 offset:33408
	s_waitcnt lgkmcnt(3)
	v_mfma_f32_16x16x32_bf16 v[84:87], v[140:143], v[168:171], v[84:87]
	v_mfma_f32_16x16x32_bf16 v[54:57], v[152:155], v[168:171], v[54:57]
	v_mfma_f32_16x16x32_bf16 v[34:37], v[156:159], v[168:171], v[34:37]
	v_mfma_f32_16x16x32_bf16 v[14:17], v[160:163], v[168:171], v[14:17]
	ds_read_b128 v[168:171], v151 offset:50048
	s_waitcnt lgkmcnt(3)
	v_mfma_f32_16x16x32_bf16 v[70:73], v[140:143], v[176:179], v[70:73]
	v_mfma_f32_16x16x32_bf16 v[50:53], v[152:155], v[176:179], v[50:53]
	v_mfma_f32_16x16x32_bf16 v[30:33], v[156:159], v[176:179], v[30:33]
	v_mfma_f32_16x16x32_bf16 v[10:13], v[160:163], v[176:179], v[10:13]
	ds_read_b128 v[176:179], v138 offset:128
	global_load_dwordx4 v[74:77], v239, s[36:37] offset:384
	global_load_dwordx4 v[140:143], v239, s[36:37] offset:448
	global_load_dwordx4 v[96:99], v239, s[38:39] offset:384
	global_load_dwordx4 v[152:155], v239, s[38:39] offset:448
	global_load_dwordx4 v[92:95], v239, s[40:41] offset:384
	global_load_dwordx4 v[156:159], v239, s[40:41] offset:448
	global_load_dwordx4 v[88:91], v239, s[44:45] offset:384
	global_load_dwordx4 v[160:163], v239, s[44:45] offset:448
	s_waitcnt vmcnt(33)
	s_waitcnt lgkmcnt(3)
	v_mfma_f32_16x16x32_bf16 v[100:103], v[180:183], v[164:167], v[100:103]
	v_mfma_f32_16x16x32_bf16 v[62:65], v[184:187], v[164:167], v[62:65]
	v_mfma_f32_16x16x32_bf16 v[42:45], v[188:191], v[164:167], v[42:45]
	v_mfma_f32_16x16x32_bf16 v[22:25], v[192:195], v[164:167], v[22:25]
	ds_read_b128 v[164:167], v151 offset:16832
	s_waitcnt lgkmcnt(3)
	v_mfma_f32_16x16x32_bf16 v[80:83], v[180:183], v[172:175], v[80:83]
	v_mfma_f32_16x16x32_bf16 v[58:61], v[184:187], v[172:175], v[58:61]
	v_mfma_f32_16x16x32_bf16 v[38:41], v[188:191], v[172:175], v[38:41]
	v_mfma_f32_16x16x32_bf16 v[18:21], v[192:195], v[172:175], v[18:21]
	ds_read_b128 v[172:175], v151 offset:33472
	s_waitcnt lgkmcnt(3)
	v_mfma_f32_16x16x32_bf16 v[84:87], v[180:183], v[168:171], v[84:87]
	v_mfma_f32_16x16x32_bf16 v[54:57], v[184:187], v[168:171], v[54:57]
	v_mfma_f32_16x16x32_bf16 v[34:37], v[188:191], v[168:171], v[34:37]
	v_mfma_f32_16x16x32_bf16 v[14:17], v[192:195], v[168:171], v[14:17]
	ds_read_b128 v[168:171], v151 offset:50112
	s_waitcnt lgkmcnt(3)
	v_mfma_f32_16x16x32_bf16 v[70:73], v[180:183], v[176:179], v[70:73]
	v_mfma_f32_16x16x32_bf16 v[50:53], v[184:187], v[176:179], v[50:53]
	v_mfma_f32_16x16x32_bf16 v[30:33], v[188:191], v[176:179], v[30:33]
	v_mfma_f32_16x16x32_bf16 v[10:13], v[192:195], v[176:179], v[10:13]
	ds_read_b128 v[176:179], v138 offset:192
	s_waitcnt vmcnt(32)
	s_waitcnt lgkmcnt(3)
	v_mfma_f32_16x16x32_bf16 v[100:103], v[196:199], v[164:167], v[100:103]
	v_mfma_f32_16x16x32_bf16 v[62:65], v[200:203], v[164:167], v[62:65]
	v_mfma_f32_16x16x32_bf16 v[42:45], v[204:207], v[164:167], v[42:45]
	v_mfma_f32_16x16x32_bf16 v[22:25], v[208:211], v[164:167], v[22:25]
	ds_read_b128 v[164:167], v151 offset:16896
	s_waitcnt lgkmcnt(3)
	v_mfma_f32_16x16x32_bf16 v[80:83], v[196:199], v[172:175], v[80:83]
	v_mfma_f32_16x16x32_bf16 v[58:61], v[200:203], v[172:175], v[58:61]
	v_mfma_f32_16x16x32_bf16 v[38:41], v[204:207], v[172:175], v[38:41]
	v_mfma_f32_16x16x32_bf16 v[18:21], v[208:211], v[172:175], v[18:21]
	ds_read_b128 v[172:175], v151 offset:33536
	s_waitcnt lgkmcnt(3)
	v_mfma_f32_16x16x32_bf16 v[84:87], v[196:199], v[168:171], v[84:87]
	v_mfma_f32_16x16x32_bf16 v[54:57], v[200:203], v[168:171], v[54:57]
	v_mfma_f32_16x16x32_bf16 v[34:37], v[204:207], v[168:171], v[34:37]
	v_mfma_f32_16x16x32_bf16 v[14:17], v[208:211], v[168:171], v[14:17]
	ds_read_b128 v[168:171], v151 offset:50176
	s_waitcnt lgkmcnt(3)
	v_mfma_f32_16x16x32_bf16 v[70:73], v[196:199], v[176:179], v[70:73]
	v_mfma_f32_16x16x32_bf16 v[50:53], v[200:203], v[176:179], v[50:53]
	v_mfma_f32_16x16x32_bf16 v[30:33], v[204:207], v[176:179], v[30:33]
	v_mfma_f32_16x16x32_bf16 v[10:13], v[208:211], v[176:179], v[10:13]
	ds_read_b128 v[176:179], v138 offset:256
	global_load_dwordx4 v[180:183], v239, s[36:37] offset:512
	global_load_dwordx4 v[196:199], v239, s[36:37] offset:576
	global_load_dwordx4 v[184:187], v239, s[38:39] offset:512
	global_load_dwordx4 v[200:203], v239, s[38:39] offset:576
	global_load_dwordx4 v[188:191], v239, s[40:41] offset:512
	global_load_dwordx4 v[204:207], v239, s[40:41] offset:576
	global_load_dwordx4 v[192:195], v239, s[44:45] offset:512
	global_load_dwordx4 v[208:211], v239, s[44:45] offset:576
	s_waitcnt vmcnt(33)
	s_waitcnt lgkmcnt(3)
	v_mfma_f32_16x16x32_bf16 v[100:103], v[212:215], v[164:167], v[100:103]
	v_mfma_f32_16x16x32_bf16 v[62:65], v[216:219], v[164:167], v[62:65]
	v_mfma_f32_16x16x32_bf16 v[42:45], v[240:243], v[164:167], v[42:45]
	v_mfma_f32_16x16x32_bf16 v[22:25], v[244:247], v[164:167], v[22:25]
	ds_read_b128 v[164:167], v151 offset:16960
	s_waitcnt lgkmcnt(3)
	v_mfma_f32_16x16x32_bf16 v[80:83], v[212:215], v[172:175], v[80:83]
	v_mfma_f32_16x16x32_bf16 v[58:61], v[216:219], v[172:175], v[58:61]
	v_mfma_f32_16x16x32_bf16 v[38:41], v[240:243], v[172:175], v[38:41]
	v_mfma_f32_16x16x32_bf16 v[18:21], v[244:247], v[172:175], v[18:21]
	ds_read_b128 v[172:175], v151 offset:33600
	s_waitcnt lgkmcnt(3)
	v_mfma_f32_16x16x32_bf16 v[84:87], v[212:215], v[168:171], v[84:87]
	v_mfma_f32_16x16x32_bf16 v[54:57], v[216:219], v[168:171], v[54:57]
	v_mfma_f32_16x16x32_bf16 v[34:37], v[240:243], v[168:171], v[34:37]
	v_mfma_f32_16x16x32_bf16 v[14:17], v[244:247], v[168:171], v[14:17]
	ds_read_b128 v[168:171], v151 offset:50240
	s_waitcnt lgkmcnt(3)
	v_mfma_f32_16x16x32_bf16 v[70:73], v[212:215], v[176:179], v[70:73]
	v_mfma_f32_16x16x32_bf16 v[50:53], v[216:219], v[176:179], v[50:53]
	v_mfma_f32_16x16x32_bf16 v[30:33], v[240:243], v[176:179], v[30:33]
	v_mfma_f32_16x16x32_bf16 v[10:13], v[244:247], v[176:179], v[10:13]
	ds_read_b128 v[176:179], v138 offset:320
	s_waitcnt vmcnt(32)
	s_waitcnt lgkmcnt(3)
	v_mfma_f32_16x16x32_bf16 v[100:103], v[66:69], v[164:167], v[100:103]
	v_mfma_f32_16x16x32_bf16 v[62:65], v[46:49], v[164:167], v[62:65]
	v_mfma_f32_16x16x32_bf16 v[42:45], v[26:29], v[164:167], v[42:45]
	v_mfma_f32_16x16x32_bf16 v[22:25], v[6:9], v[164:167], v[22:25]
	ds_read_b128 v[164:167], v151 offset:17024
	s_waitcnt lgkmcnt(3)
	v_mfma_f32_16x16x32_bf16 v[80:83], v[66:69], v[172:175], v[80:83]
	v_mfma_f32_16x16x32_bf16 v[58:61], v[46:49], v[172:175], v[58:61]
	v_mfma_f32_16x16x32_bf16 v[38:41], v[26:29], v[172:175], v[38:41]
	v_mfma_f32_16x16x32_bf16 v[18:21], v[6:9], v[172:175], v[18:21]
	ds_read_b128 v[172:175], v151 offset:33664
	s_waitcnt lgkmcnt(3)
	v_mfma_f32_16x16x32_bf16 v[84:87], v[66:69], v[168:171], v[84:87]
	v_mfma_f32_16x16x32_bf16 v[54:57], v[46:49], v[168:171], v[54:57]
	v_mfma_f32_16x16x32_bf16 v[34:37], v[26:29], v[168:171], v[34:37]
	v_mfma_f32_16x16x32_bf16 v[14:17], v[6:9], v[168:171], v[14:17]
	ds_read_b128 v[168:171], v151 offset:50304
	s_waitcnt lgkmcnt(3)
	v_mfma_f32_16x16x32_bf16 v[70:73], v[66:69], v[176:179], v[70:73]
	v_mfma_f32_16x16x32_bf16 v[50:53], v[46:49], v[176:179], v[50:53]
	v_mfma_f32_16x16x32_bf16 v[30:33], v[26:29], v[176:179], v[30:33]
	v_mfma_f32_16x16x32_bf16 v[10:13], v[6:9], v[176:179], v[10:13]
	ds_read_b128 v[176:179], v138 offset:384
	global_load_dwordx4 v[212:215], v239, s[36:37] offset:640
	global_load_dwordx4 v[66:69], v239, s[36:37] offset:704
	global_load_dwordx4 v[216:219], v239, s[38:39] offset:640
	global_load_dwordx4 v[46:49], v239, s[38:39] offset:704
	global_load_dwordx4 v[240:243], v239, s[40:41] offset:640
	global_load_dwordx4 v[26:29], v239, s[40:41] offset:704
	global_load_dwordx4 v[244:247], v239, s[44:45] offset:640
	global_load_dwordx4 v[6:9], v239, s[44:45] offset:704
	s_waitcnt vmcnt(17)
	s_waitcnt lgkmcnt(3)
	v_mfma_f32_16x16x32_bf16 v[100:103], v[74:77], v[164:167], v[100:103]
	v_mfma_f32_16x16x32_bf16 v[62:65], v[96:99], v[164:167], v[62:65]
	v_mfma_f32_16x16x32_bf16 v[42:45], v[92:95], v[164:167], v[42:45]
	v_mfma_f32_16x16x32_bf16 v[22:25], v[88:91], v[164:167], v[22:25]
	ds_read_b128 v[164:167], v151 offset:17088
	s_waitcnt lgkmcnt(3)
	v_mfma_f32_16x16x32_bf16 v[80:83], v[74:77], v[172:175], v[80:83]
	v_mfma_f32_16x16x32_bf16 v[58:61], v[96:99], v[172:175], v[58:61]
	v_mfma_f32_16x16x32_bf16 v[38:41], v[92:95], v[172:175], v[38:41]
	v_mfma_f32_16x16x32_bf16 v[18:21], v[88:91], v[172:175], v[18:21]
	ds_read_b128 v[172:175], v151 offset:33728
	s_waitcnt lgkmcnt(3)
	v_mfma_f32_16x16x32_bf16 v[84:87], v[74:77], v[168:171], v[84:87]
	v_mfma_f32_16x16x32_bf16 v[54:57], v[96:99], v[168:171], v[54:57]
	v_mfma_f32_16x16x32_bf16 v[34:37], v[92:95], v[168:171], v[34:37]
	v_mfma_f32_16x16x32_bf16 v[14:17], v[88:91], v[168:171], v[14:17]
	ds_read_b128 v[168:171], v151 offset:50368
	s_waitcnt lgkmcnt(3)
	v_mfma_f32_16x16x32_bf16 v[70:73], v[74:77], v[176:179], v[70:73]
	v_mfma_f32_16x16x32_bf16 v[50:53], v[96:99], v[176:179], v[50:53]
	v_mfma_f32_16x16x32_bf16 v[30:33], v[92:95], v[176:179], v[30:33]
	v_mfma_f32_16x16x32_bf16 v[10:13], v[88:91], v[176:179], v[10:13]
	ds_read_b128 v[176:179], v138 offset:448
	s_waitcnt vmcnt(16)
	s_waitcnt lgkmcnt(3)
	v_mfma_f32_16x16x32_bf16 v[100:103], v[140:143], v[164:167], v[100:103]
	v_mfma_f32_16x16x32_bf16 v[62:65], v[152:155], v[164:167], v[62:65]
	v_mfma_f32_16x16x32_bf16 v[42:45], v[156:159], v[164:167], v[42:45]
	v_mfma_f32_16x16x32_bf16 v[22:25], v[160:163], v[164:167], v[22:25]
	ds_read_b128 v[164:167], v151 offset:17152
	s_waitcnt lgkmcnt(3)
	v_mfma_f32_16x16x32_bf16 v[80:83], v[140:143], v[172:175], v[80:83]
	v_mfma_f32_16x16x32_bf16 v[58:61], v[152:155], v[172:175], v[58:61]
	v_mfma_f32_16x16x32_bf16 v[38:41], v[156:159], v[172:175], v[38:41]
	v_mfma_f32_16x16x32_bf16 v[18:21], v[160:163], v[172:175], v[18:21]
	ds_read_b128 v[172:175], v151 offset:33792
	s_waitcnt lgkmcnt(3)
	v_mfma_f32_16x16x32_bf16 v[84:87], v[140:143], v[168:171], v[84:87]
	v_mfma_f32_16x16x32_bf16 v[54:57], v[152:155], v[168:171], v[54:57]
	v_mfma_f32_16x16x32_bf16 v[34:37], v[156:159], v[168:171], v[34:37]
	v_mfma_f32_16x16x32_bf16 v[14:17], v[160:163], v[168:171], v[14:17]
	ds_read_b128 v[168:171], v151 offset:50432
	s_waitcnt lgkmcnt(3)
	v_mfma_f32_16x16x32_bf16 v[70:73], v[140:143], v[176:179], v[70:73]
	v_mfma_f32_16x16x32_bf16 v[50:53], v[152:155], v[176:179], v[50:53]
	v_mfma_f32_16x16x32_bf16 v[30:33], v[156:159], v[176:179], v[30:33]
	v_mfma_f32_16x16x32_bf16 v[10:13], v[160:163], v[176:179], v[10:13]
	ds_read_b128 v[176:179], v138 offset:512
	global_load_dwordx4 v[74:77], v239, s[36:37] offset:768
	global_load_dwordx4 v[140:143], v239, s[36:37] offset:832
	global_load_dwordx4 v[96:99], v239, s[38:39] offset:768
	global_load_dwordx4 v[152:155], v239, s[38:39] offset:832
	global_load_dwordx4 v[92:95], v239, s[40:41] offset:768
	global_load_dwordx4 v[156:159], v239, s[40:41] offset:832
	global_load_dwordx4 v[88:91], v239, s[44:45] offset:768
	global_load_dwordx4 v[160:163], v239, s[44:45] offset:832
	s_waitcnt vmcnt(17)
	s_waitcnt lgkmcnt(3)
	v_mfma_f32_16x16x32_bf16 v[100:103], v[180:183], v[164:167], v[100:103]
	v_mfma_f32_16x16x32_bf16 v[62:65], v[184:187], v[164:167], v[62:65]
	v_mfma_f32_16x16x32_bf16 v[42:45], v[188:191], v[164:167], v[42:45]
	v_mfma_f32_16x16x32_bf16 v[22:25], v[192:195], v[164:167], v[22:25]
	ds_read_b128 v[164:167], v151 offset:17216
	s_waitcnt lgkmcnt(3)
	v_mfma_f32_16x16x32_bf16 v[80:83], v[180:183], v[172:175], v[80:83]
	v_mfma_f32_16x16x32_bf16 v[58:61], v[184:187], v[172:175], v[58:61]
	v_mfma_f32_16x16x32_bf16 v[38:41], v[188:191], v[172:175], v[38:41]
	v_mfma_f32_16x16x32_bf16 v[18:21], v[192:195], v[172:175], v[18:21]
	ds_read_b128 v[172:175], v151 offset:33856
	s_waitcnt lgkmcnt(3)
	v_mfma_f32_16x16x32_bf16 v[84:87], v[180:183], v[168:171], v[84:87]
	v_mfma_f32_16x16x32_bf16 v[54:57], v[184:187], v[168:171], v[54:57]
	v_mfma_f32_16x16x32_bf16 v[34:37], v[188:191], v[168:171], v[34:37]
	v_mfma_f32_16x16x32_bf16 v[14:17], v[192:195], v[168:171], v[14:17]
	ds_read_b128 v[168:171], v151 offset:50496
	s_waitcnt lgkmcnt(3)
	v_mfma_f32_16x16x32_bf16 v[70:73], v[180:183], v[176:179], v[70:73]
	v_mfma_f32_16x16x32_bf16 v[50:53], v[184:187], v[176:179], v[50:53]
	v_mfma_f32_16x16x32_bf16 v[30:33], v[188:191], v[176:179], v[30:33]
	v_mfma_f32_16x16x32_bf16 v[10:13], v[192:195], v[176:179], v[10:13]
	ds_read_b128 v[176:179], v138 offset:576
	s_waitcnt vmcnt(16)
	s_waitcnt lgkmcnt(3)
	v_mfma_f32_16x16x32_bf16 v[100:103], v[196:199], v[164:167], v[100:103]
	v_mfma_f32_16x16x32_bf16 v[62:65], v[200:203], v[164:167], v[62:65]
	v_mfma_f32_16x16x32_bf16 v[42:45], v[204:207], v[164:167], v[42:45]
	v_mfma_f32_16x16x32_bf16 v[22:25], v[208:211], v[164:167], v[22:25]
	ds_read_b128 v[164:167], v151 offset:17280
	s_waitcnt lgkmcnt(3)
	v_mfma_f32_16x16x32_bf16 v[80:83], v[196:199], v[172:175], v[80:83]
	v_mfma_f32_16x16x32_bf16 v[58:61], v[200:203], v[172:175], v[58:61]
	v_mfma_f32_16x16x32_bf16 v[38:41], v[204:207], v[172:175], v[38:41]
	v_mfma_f32_16x16x32_bf16 v[18:21], v[208:211], v[172:175], v[18:21]
	ds_read_b128 v[172:175], v151 offset:33920
	s_waitcnt lgkmcnt(3)
	v_mfma_f32_16x16x32_bf16 v[84:87], v[196:199], v[168:171], v[84:87]
	v_mfma_f32_16x16x32_bf16 v[54:57], v[200:203], v[168:171], v[54:57]
	v_mfma_f32_16x16x32_bf16 v[34:37], v[204:207], v[168:171], v[34:37]
	v_mfma_f32_16x16x32_bf16 v[14:17], v[208:211], v[168:171], v[14:17]
	ds_read_b128 v[168:171], v151 offset:50560
	s_waitcnt lgkmcnt(3)
	v_mfma_f32_16x16x32_bf16 v[70:73], v[196:199], v[176:179], v[70:73]
	v_mfma_f32_16x16x32_bf16 v[50:53], v[200:203], v[176:179], v[50:53]
	v_mfma_f32_16x16x32_bf16 v[30:33], v[204:207], v[176:179], v[30:33]
	v_mfma_f32_16x16x32_bf16 v[10:13], v[208:211], v[176:179], v[10:13]
	ds_read_b128 v[176:179], v138 offset:640
	global_load_dwordx4 v[180:183], v239, s[36:37] offset:896
	global_load_dwordx4 v[196:199], v239, s[36:37] offset:960
	global_load_dwordx4 v[184:187], v239, s[38:39] offset:896
	global_load_dwordx4 v[200:203], v239, s[38:39] offset:960
	global_load_dwordx4 v[188:191], v239, s[40:41] offset:896
	global_load_dwordx4 v[204:207], v239, s[40:41] offset:960
	global_load_dwordx4 v[192:195], v239, s[44:45] offset:896
	global_load_dwordx4 v[208:211], v239, s[44:45] offset:960
	s_waitcnt vmcnt(17)
	s_waitcnt lgkmcnt(3)
	v_mfma_f32_16x16x32_bf16 v[100:103], v[212:215], v[164:167], v[100:103]
	v_mfma_f32_16x16x32_bf16 v[62:65], v[216:219], v[164:167], v[62:65]
	v_mfma_f32_16x16x32_bf16 v[42:45], v[240:243], v[164:167], v[42:45]
	v_mfma_f32_16x16x32_bf16 v[22:25], v[244:247], v[164:167], v[22:25]
	ds_read_b128 v[164:167], v151 offset:17344
	s_waitcnt lgkmcnt(3)
	v_mfma_f32_16x16x32_bf16 v[80:83], v[212:215], v[172:175], v[80:83]
	v_mfma_f32_16x16x32_bf16 v[58:61], v[216:219], v[172:175], v[58:61]
	v_mfma_f32_16x16x32_bf16 v[38:41], v[240:243], v[172:175], v[38:41]
	v_mfma_f32_16x16x32_bf16 v[18:21], v[244:247], v[172:175], v[18:21]
	ds_read_b128 v[172:175], v151 offset:33984
	s_waitcnt lgkmcnt(3)
	v_mfma_f32_16x16x32_bf16 v[84:87], v[212:215], v[168:171], v[84:87]
	v_mfma_f32_16x16x32_bf16 v[54:57], v[216:219], v[168:171], v[54:57]
	v_mfma_f32_16x16x32_bf16 v[34:37], v[240:243], v[168:171], v[34:37]
	v_mfma_f32_16x16x32_bf16 v[14:17], v[244:247], v[168:171], v[14:17]
	ds_read_b128 v[168:171], v151 offset:50624
	s_waitcnt lgkmcnt(3)
	v_mfma_f32_16x16x32_bf16 v[70:73], v[212:215], v[176:179], v[70:73]
	v_mfma_f32_16x16x32_bf16 v[50:53], v[216:219], v[176:179], v[50:53]
	v_mfma_f32_16x16x32_bf16 v[30:33], v[240:243], v[176:179], v[30:33]
	v_mfma_f32_16x16x32_bf16 v[10:13], v[244:247], v[176:179], v[10:13]
	ds_read_b128 v[176:179], v138 offset:704
	s_waitcnt vmcnt(16)
	s_waitcnt lgkmcnt(3)
	v_mfma_f32_16x16x32_bf16 v[100:103], v[66:69], v[164:167], v[100:103]
	v_mfma_f32_16x16x32_bf16 v[62:65], v[46:49], v[164:167], v[62:65]
	v_mfma_f32_16x16x32_bf16 v[42:45], v[26:29], v[164:167], v[42:45]
	v_mfma_f32_16x16x32_bf16 v[22:25], v[6:9], v[164:167], v[22:25]
	ds_read_b128 v[164:167], v151 offset:17408
	s_waitcnt lgkmcnt(3)
	v_mfma_f32_16x16x32_bf16 v[80:83], v[66:69], v[172:175], v[80:83]
	v_mfma_f32_16x16x32_bf16 v[58:61], v[46:49], v[172:175], v[58:61]
	v_mfma_f32_16x16x32_bf16 v[38:41], v[26:29], v[172:175], v[38:41]
	v_mfma_f32_16x16x32_bf16 v[18:21], v[6:9], v[172:175], v[18:21]
	ds_read_b128 v[172:175], v151 offset:34048
	s_waitcnt lgkmcnt(3)
	v_mfma_f32_16x16x32_bf16 v[84:87], v[66:69], v[168:171], v[84:87]
	v_mfma_f32_16x16x32_bf16 v[54:57], v[46:49], v[168:171], v[54:57]
	v_mfma_f32_16x16x32_bf16 v[34:37], v[26:29], v[168:171], v[34:37]
	v_mfma_f32_16x16x32_bf16 v[14:17], v[6:9], v[168:171], v[14:17]
	ds_read_b128 v[168:171], v151 offset:50688
	s_waitcnt lgkmcnt(3)
	v_mfma_f32_16x16x32_bf16 v[70:73], v[66:69], v[176:179], v[70:73]
	v_mfma_f32_16x16x32_bf16 v[50:53], v[46:49], v[176:179], v[50:53]
	v_mfma_f32_16x16x32_bf16 v[30:33], v[26:29], v[176:179], v[30:33]
	v_mfma_f32_16x16x32_bf16 v[10:13], v[6:9], v[176:179], v[10:13]
	ds_read_b128 v[176:179], v138 offset:768
	global_load_dwordx4 v[66:69], v220, s[46:47]
	global_load_dwordx4 v[46:49], v220, s[46:47] offset:64
	global_load_dwordx4 v[26:29], v220, s[46:47] offset:128
	global_load_dwordx4 v[6:9], v220, s[46:47] offset:192
	s_waitcnt vmcnt(13)
	s_waitcnt lgkmcnt(3)
	v_mfma_f32_16x16x32_bf16 v[100:103], v[74:77], v[164:167], v[100:103]
	v_mfma_f32_16x16x32_bf16 v[62:65], v[96:99], v[164:167], v[62:65]
	v_mfma_f32_16x16x32_bf16 v[42:45], v[92:95], v[164:167], v[42:45]
	v_mfma_f32_16x16x32_bf16 v[22:25], v[88:91], v[164:167], v[22:25]
	ds_read_b128 v[164:167], v151 offset:17472
	s_waitcnt lgkmcnt(3)
	v_mfma_f32_16x16x32_bf16 v[80:83], v[74:77], v[172:175], v[80:83]
	v_mfma_f32_16x16x32_bf16 v[58:61], v[96:99], v[172:175], v[58:61]
	v_mfma_f32_16x16x32_bf16 v[38:41], v[92:95], v[172:175], v[38:41]
	v_mfma_f32_16x16x32_bf16 v[18:21], v[88:91], v[172:175], v[18:21]
	ds_read_b128 v[172:175], v151 offset:34112
	s_waitcnt lgkmcnt(3)
	v_mfma_f32_16x16x32_bf16 v[84:87], v[74:77], v[168:171], v[84:87]
	v_mfma_f32_16x16x32_bf16 v[54:57], v[96:99], v[168:171], v[54:57]
	v_mfma_f32_16x16x32_bf16 v[34:37], v[92:95], v[168:171], v[34:37]
	v_mfma_f32_16x16x32_bf16 v[14:17], v[88:91], v[168:171], v[14:17]
	ds_read_b128 v[168:171], v151 offset:50752
	s_waitcnt lgkmcnt(3)
	v_mfma_f32_16x16x32_bf16 v[70:73], v[74:77], v[176:179], v[70:73]
	v_mfma_f32_16x16x32_bf16 v[50:53], v[96:99], v[176:179], v[50:53]
	v_mfma_f32_16x16x32_bf16 v[30:33], v[92:95], v[176:179], v[30:33]
	v_mfma_f32_16x16x32_bf16 v[10:13], v[88:91], v[176:179], v[10:13]
	ds_read_b128 v[176:179], v138 offset:832
	s_waitcnt vmcnt(12)
	s_waitcnt lgkmcnt(3)
	v_mfma_f32_16x16x32_bf16 v[100:103], v[140:143], v[164:167], v[100:103]
	v_mfma_f32_16x16x32_bf16 v[62:65], v[152:155], v[164:167], v[62:65]
	v_mfma_f32_16x16x32_bf16 v[42:45], v[156:159], v[164:167], v[42:45]
	v_mfma_f32_16x16x32_bf16 v[22:25], v[160:163], v[164:167], v[22:25]
	ds_read_b128 v[164:167], v151 offset:17536
	s_waitcnt lgkmcnt(3)
	v_mfma_f32_16x16x32_bf16 v[80:83], v[140:143], v[172:175], v[80:83]
	v_mfma_f32_16x16x32_bf16 v[58:61], v[152:155], v[172:175], v[58:61]
	v_mfma_f32_16x16x32_bf16 v[38:41], v[156:159], v[172:175], v[38:41]
	v_mfma_f32_16x16x32_bf16 v[18:21], v[160:163], v[172:175], v[18:21]
	ds_read_b128 v[172:175], v151 offset:34176
	s_waitcnt lgkmcnt(3)
	v_mfma_f32_16x16x32_bf16 v[84:87], v[140:143], v[168:171], v[84:87]
	v_mfma_f32_16x16x32_bf16 v[54:57], v[152:155], v[168:171], v[54:57]
	v_mfma_f32_16x16x32_bf16 v[34:37], v[156:159], v[168:171], v[34:37]
	v_mfma_f32_16x16x32_bf16 v[14:17], v[160:163], v[168:171], v[14:17]
	ds_read_b128 v[168:171], v151 offset:50816
	s_waitcnt lgkmcnt(3)
	v_mfma_f32_16x16x32_bf16 v[70:73], v[140:143], v[176:179], v[70:73]
	v_mfma_f32_16x16x32_bf16 v[50:53], v[152:155], v[176:179], v[50:53]
	v_mfma_f32_16x16x32_bf16 v[30:33], v[156:159], v[176:179], v[30:33]
	v_mfma_f32_16x16x32_bf16 v[10:13], v[160:163], v[176:179], v[10:13]
	ds_read_b128 v[176:179], v138 offset:896
	s_waitcnt vmcnt(5)
	s_waitcnt lgkmcnt(3)
	v_mfma_f32_16x16x32_bf16 v[100:103], v[180:183], v[164:167], v[100:103]
	v_mfma_f32_16x16x32_bf16 v[62:65], v[184:187], v[164:167], v[62:65]
	v_mfma_f32_16x16x32_bf16 v[42:45], v[188:191], v[164:167], v[42:45]
	v_mfma_f32_16x16x32_bf16 v[22:25], v[192:195], v[164:167], v[22:25]
	ds_read_b128 v[164:167], v151 offset:17600
	s_waitcnt lgkmcnt(3)
	v_mfma_f32_16x16x32_bf16 v[80:83], v[180:183], v[172:175], v[80:83]
	v_mfma_f32_16x16x32_bf16 v[58:61], v[184:187], v[172:175], v[58:61]
	v_mfma_f32_16x16x32_bf16 v[38:41], v[188:191], v[172:175], v[38:41]
	v_mfma_f32_16x16x32_bf16 v[18:21], v[192:195], v[172:175], v[18:21]
	ds_read_b128 v[172:175], v151 offset:34240
	s_waitcnt lgkmcnt(3)
	v_mfma_f32_16x16x32_bf16 v[84:87], v[180:183], v[168:171], v[84:87]
	v_mfma_f32_16x16x32_bf16 v[54:57], v[184:187], v[168:171], v[54:57]
	v_mfma_f32_16x16x32_bf16 v[34:37], v[188:191], v[168:171], v[34:37]
	v_mfma_f32_16x16x32_bf16 v[14:17], v[192:195], v[168:171], v[14:17]
	ds_read_b128 v[168:171], v151 offset:50880
	s_waitcnt lgkmcnt(3)
	v_mfma_f32_16x16x32_bf16 v[70:73], v[180:183], v[176:179], v[70:73]
	v_mfma_f32_16x16x32_bf16 v[50:53], v[184:187], v[176:179], v[50:53]
	v_mfma_f32_16x16x32_bf16 v[30:33], v[188:191], v[176:179], v[30:33]
	v_mfma_f32_16x16x32_bf16 v[10:13], v[192:195], v[176:179], v[10:13]
	ds_read_b128 v[176:179], v138 offset:960
	s_waitcnt vmcnt(4)
	s_waitcnt lgkmcnt(3)
	v_mfma_f32_16x16x32_bf16 v[100:103], v[196:199], v[164:167], v[100:103]
	v_mfma_f32_16x16x32_bf16 v[62:65], v[200:203], v[164:167], v[62:65]
	v_mfma_f32_16x16x32_bf16 v[42:45], v[204:207], v[164:167], v[42:45]
	v_mfma_f32_16x16x32_bf16 v[22:25], v[208:211], v[164:167], v[22:25]
	s_waitcnt lgkmcnt(2)
	v_mfma_f32_16x16x32_bf16 v[80:83], v[196:199], v[172:175], v[80:83]
	v_mfma_f32_16x16x32_bf16 v[58:61], v[200:203], v[172:175], v[58:61]
	v_mfma_f32_16x16x32_bf16 v[38:41], v[204:207], v[172:175], v[38:41]
	v_mfma_f32_16x16x32_bf16 v[18:21], v[208:211], v[172:175], v[18:21]
	s_waitcnt lgkmcnt(1)
	v_mfma_f32_16x16x32_bf16 v[84:87], v[196:199], v[168:171], v[84:87]
	v_mfma_f32_16x16x32_bf16 v[54:57], v[200:203], v[168:171], v[54:57]
	v_mfma_f32_16x16x32_bf16 v[34:37], v[204:207], v[168:171], v[34:37]
	v_mfma_f32_16x16x32_bf16 v[14:17], v[208:211], v[168:171], v[14:17]
	s_waitcnt lgkmcnt(0)
	v_mfma_f32_16x16x32_bf16 v[70:73], v[196:199], v[176:179], v[70:73]
	v_mfma_f32_16x16x32_bf16 v[50:53], v[200:203], v[176:179], v[50:53]
	v_mfma_f32_16x16x32_bf16 v[30:33], v[204:207], v[176:179], v[30:33]
	v_mfma_f32_16x16x32_bf16 v[10:13], v[208:211], v[176:179], v[10:13]
	s_waitcnt vmcnt(3)
	v_add_f32_e32 v76, v66, v100
	v_mul_f32_e32 v76, 0xbfb8aa3b, v76
	v_exp_f32_e32 v76, v76
	s_waitcnt vmcnt(1)
	v_lshlrev_b32_e32 v94, 16, v78
	s_waitcnt vmcnt(0)
	v_or_b32_e32 v88, s0, v146
	v_lshlrev_b32_e32 v74, 1, v88
	v_add_f32_e32 v76, 1.0, v76
	v_rcp_f32_e32 v90, v76
	v_add_f32_e32 v76, v67, v101
	v_mul_f32_e32 v76, 0xbfb8aa3b, v76
	v_exp_f32_e32 v76, v76
	v_add_u32_e32 v75, v150, v74
	v_lshlrev_b32_e32 v95, 16, v79
	v_add_u32_e32 v97, 0x4000, v75
	v_add_f32_e32 v76, 1.0, v76
	v_rcp_f32_e32 v92, v76
	v_add_f32_e32 v76, v68, v102
	v_mul_f32_e32 v76, 0xbfb8aa3b, v76
	v_exp_f32_e32 v76, v76
	v_mul_f32_e32 v75, 0xbfb8aa3b, v95
	v_exp_f32_e32 v75, v75
	v_and_b32_e32 v100, 0xffff0000, v78
	v_add_f32_e32 v76, 1.0, v76
	v_rcp_f32_e32 v91, v76
	v_add_f32_e32 v76, v69, v103
	v_mul_f32_e32 v76, 0xbfb8aa3b, v76
	v_exp_f32_e32 v76, v76
	v_and_b32_e32 v101, 0xffff0000, v79
	v_add_f32_e32 v75, 1.0, v75
	v_rcp_f32_e32 v99, v75
	v_add_f32_e32 v76, 1.0, v76
	v_rcp_f32_e32 v93, v76
	v_mul_f32_e32 v76, 0xbfb8aa3b, v94
	v_exp_f32_e32 v76, v76
	v_mul_f32_e32 v75, 0xbfb8aa3b, v101
	v_exp_f32_e32 v75, v75
	v_ashrrev_i32_e32 v89, 31, v88
	v_add_f32_e32 v76, 1.0, v76
	v_rcp_f32_e32 v98, v76
	v_mul_f32_e32 v76, 0xbfb8aa3b, v100
	v_exp_f32_e32 v76, v76
	v_add_f32_e32 v75, 1.0, v75
	v_rcp_f32_e32 v103, v75
	v_pk_mul_f32 v[94:95], v[98:99], v[94:95]
	v_add_f32_e32 v76, 1.0, v76
	v_rcp_f32_e32 v102, v76
	ds_read2_b64 v[76:79], v97 offset0:32 offset1:36
	v_lshlrev_b32_e32 v98, 16, v132
	v_lshlrev_b32_e32 v99, 16, v133
	v_readlane_b32 s0, v251, 55
	v_readlane_b32 s1, v251, 56
	s_waitcnt lgkmcnt(0)
	v_lshlrev_b32_e32 v137, 16, v77
	v_lshlrev_b32_e32 v136, 16, v76
	v_pk_mul_f32 v[90:91], v[90:91], v[136:137]
	v_and_b32_e32 v77, 0xffff0000, v77
	v_and_b32_e32 v76, 0xffff0000, v76
	v_pk_mul_f32 v[90:91], v[94:95], v[90:91]
	v_pk_mul_f32 v[76:77], v[92:93], v[76:77]
	v_pk_mul_f32 v[92:93], v[102:103], v[100:101]
	s_nop 0
	v_pk_mul_f32 v[76:77], v[92:93], v[76:77]
	s_nop 0
	v_cvt_pk_bf16_f32 v77, v91, v77
	v_cvt_pk_bf16_f32 v76, v90, v76
	v_lshlrev_b64 v[90:91], 1, v[88:89]
	v_lshl_add_u64 v[88:89], v[134:135], 0, v[90:91]
	global_store_dwordx2 v[88:89], v[76:77], off offset:2560
	v_add_f32_e32 v76, v66, v80
	v_add_f32_e32 v80, v69, v83
	v_mul_f32_e32 v80, 0xbfb8aa3b, v80
	v_exp_f32_e32 v80, v80
	v_add_f32_e32 v77, v67, v81
	v_mul_f32_e32 v77, 0xbfb8aa3b, v77
	v_add3_u32 v75, 0, v236, v74
	v_add_f32_e32 v80, 1.0, v80
	v_rcp_f32_e32 v93, v80
	v_mul_f32_e32 v80, 0xbfb8aa3b, v98
	v_exp_f32_e32 v80, v80
	v_exp_f32_e32 v77, v77
	v_add_u32_e32 v94, 0x4000, v75
	v_mul_f32_e32 v75, 0xbfb8aa3b, v99
	v_exp_f32_e32 v75, v75
	v_add_f32_e32 v80, 1.0, v80
	v_and_b32_e32 v102, 0xffff0000, v132
	v_add_f32_e32 v77, 1.0, v77
	v_rcp_f32_e32 v100, v80
	v_mul_f32_e32 v80, 0xbfb8aa3b, v102
	v_rcp_f32_e32 v92, v77
	v_add_f32_e32 v77, v68, v82
	v_exp_f32_e32 v80, v80
	v_mul_f32_e32 v76, 0xbfb8aa3b, v76
	v_mul_f32_e32 v77, 0xbfb8aa3b, v77
	v_and_b32_e32 v103, 0xffff0000, v133
	v_add_f32_e32 v75, 1.0, v75
	v_exp_f32_e32 v76, v76
	v_exp_f32_e32 v77, v77
	v_rcp_f32_e32 v101, v75
	v_mul_f32_e32 v75, 0xbfb8aa3b, v103
	v_exp_f32_e32 v75, v75
	v_add_f32_e32 v80, 1.0, v80
	v_rcp_f32_e32 v132, v80
	ds_read2_b64 v[80:83], v94 offset0:32 offset1:36
	v_add_f32_e32 v76, 1.0, v76
	v_add_f32_e32 v77, 1.0, v77
	v_rcp_f32_e32 v76, v76
	v_rcp_f32_e32 v77, v77
	v_add_f32_e32 v75, 1.0, v75
	v_rcp_f32_e32 v133, v75
	s_waitcnt lgkmcnt(0)
	v_lshlrev_b32_e32 v135, 16, v81
	v_lshlrev_b32_e32 v134, 16, v80
	v_pk_mul_f32 v[76:77], v[76:77], v[134:135]
	v_pk_mul_f32 v[98:99], v[100:101], v[98:99]
	v_and_b32_e32 v81, 0xffff0000, v81
	v_and_b32_e32 v80, 0xffff0000, v80
	v_pk_mul_f32 v[76:77], v[98:99], v[76:77]
	v_pk_mul_f32 v[80:81], v[92:93], v[80:81]
	v_pk_mul_f32 v[92:93], v[132:133], v[102:103]
	s_nop 0
	v_pk_mul_f32 v[80:81], v[92:93], v[80:81]
	s_nop 0
	v_cvt_pk_bf16_f32 v77, v77, v81
	v_cvt_pk_bf16_f32 v76, v76, v80
	v_or_b32_e32 v75, s88, v147
	v_mov_b64_e32 v[92:93], s[0:1]
	s_movk_i32 s4, 0x2800
	v_or_b32_e32 v96, 32, v1
	v_mad_i64_i32 v[80:81], s[0:1], v75, s4, v[92:93]
	v_mul_u32_u24_e32 v75, 0x410, v96
	v_lshlrev_b32_e32 v98, 16, v130
	v_add3_u32 v134, 0, v75, v74
	v_add_f32_e32 v74, v66, v84
	v_mul_f32_e32 v84, 0xbfb8aa3b, v98
	v_exp_f32_e32 v84, v84
	v_add_f32_e32 v75, v67, v85
	v_and_b32_e32 v102, 0xffff0000, v130
	v_lshl_add_u64 v[80:81], v[80:81], 0, v[90:91]
	v_add_f32_e32 v84, 1.0, v84
	v_mul_f32_e32 v75, 0xbfb8aa3b, v75
	v_rcp_f32_e32 v100, v84
	v_mul_f32_e32 v84, 0xbfb8aa3b, v102
	global_store_dwordx2 v[80:81], v[76:77], off offset:2560
	v_exp_f32_e32 v75, v75
	v_add_f32_e32 v77, v69, v87
	v_exp_f32_e32 v84, v84
	v_mul_f32_e32 v77, 0xbfb8aa3b, v77
	v_exp_f32_e32 v77, v77
	v_add_f32_e32 v75, 1.0, v75
	v_add_f32_e32 v84, 1.0, v84
	v_add_u32_e32 v95, 0x4000, v134
	v_rcp_f32_e32 v76, v75
	v_add_f32_e32 v75, v68, v86
	v_rcp_f32_e32 v130, v84
	ds_read2_b64 v[84:87], v95 offset0:32 offset1:36
	v_add_f32_e32 v77, 1.0, v77
	v_lshlrev_b32_e32 v99, 16, v131
	v_mul_f32_e32 v74, 0xbfb8aa3b, v74
	v_mul_f32_e32 v75, 0xbfb8aa3b, v75
	v_rcp_f32_e32 v77, v77
	v_mul_f32_e32 v101, 0xbfb8aa3b, v99
	v_exp_f32_e32 v74, v74
	v_exp_f32_e32 v75, v75
	v_exp_f32_e32 v101, v101
	v_and_b32_e32 v103, 0xffff0000, v131
	s_waitcnt lgkmcnt(0)
	v_lshlrev_b32_e32 v133, 16, v85
	v_lshlrev_b32_e32 v132, 16, v84
	v_and_b32_e32 v85, 0xffff0000, v85
	v_and_b32_e32 v84, 0xffff0000, v84
	v_add_f32_e32 v67, v67, v71
	v_pk_mul_f32 v[76:77], v[76:77], v[84:85]
	v_mul_f32_e32 v84, 0xbfb8aa3b, v103
	v_mul_f32_e32 v67, 0xbfb8aa3b, v67
	v_add_f32_e32 v74, 1.0, v74
	v_add_f32_e32 v75, 1.0, v75
	v_add_f32_e32 v101, 1.0, v101
	v_exp_f32_e32 v84, v84
	v_exp_f32_e32 v67, v67
	v_rcp_f32_e32 v74, v74
	v_rcp_f32_e32 v75, v75
	v_rcp_f32_e32 v101, v101
	v_add_f32_e32 v84, 1.0, v84
	v_add_f32_e32 v67, 1.0, v67
	v_pk_mul_f32 v[74:75], v[74:75], v[132:133]
	v_pk_mul_f32 v[98:99], v[100:101], v[98:99]
	v_rcp_f32_e32 v131, v84
	v_add_f32_e32 v66, v66, v70
	v_rcp_f32_e32 v70, v67
	v_add_f32_e32 v67, v68, v72
	v_add_f32_e32 v68, v69, v73
	v_pk_mul_f32 v[74:75], v[98:99], v[74:75]
	v_mul_f32_e32 v68, 0xbfb8aa3b, v68
	v_and_b32_e32 v98, 0xffff0000, v128
	v_exp_f32_e32 v68, v68
	v_mul_f32_e32 v73, 0xbfb8aa3b, v98
	v_exp_f32_e32 v73, v73
	v_pk_mul_f32 v[84:85], v[130:131], v[102:103]
	v_add_f32_e32 v68, 1.0, v68
	v_pk_mul_f32 v[76:77], v[84:85], v[76:77]
	s_nop 0
	v_cvt_pk_bf16_f32 v74, v74, v76
	v_cvt_pk_bf16_f32 v75, v75, v77
	v_rcp_f32_e32 v71, v68
	v_lshlrev_b32_e32 v69, 16, v129
	v_lshlrev_b32_e32 v68, 16, v128
	v_add_f32_e32 v73, 1.0, v73
	v_mul_f32_e32 v66, 0xbfb8aa3b, v66
	v_mul_f32_e32 v67, 0xbfb8aa3b, v67
	v_mul_f32_e32 v72, 0xbfb8aa3b, v68
	v_rcp_f32_e32 v100, v73
	v_mul_f32_e32 v73, 0xbfb8aa3b, v69
	v_or_b32_e32 v76, s88, v96
	v_exp_f32_e32 v66, v66
	v_exp_f32_e32 v67, v67
	v_exp_f32_e32 v72, v72
	v_exp_f32_e32 v73, v73
	v_mad_i64_i32 v[76:77], s[0:1], v76, s4, v[92:93]
	v_lshl_add_u64 v[84:85], v[76:77], 0, v[90:91]
	v_add_u32_e32 v96, 0x8000, v134
	global_store_dwordx2 v[84:85], v[74:75], off offset:2560
	ds_read2_b64 v[74:77], v96 offset0:64 offset1:68
	v_add_f32_e32 v66, 1.0, v66
	v_add_f32_e32 v67, 1.0, v67
	v_add_f32_e32 v72, 1.0, v72
	v_add_f32_e32 v73, 1.0, v73
	v_rcp_f32_e32 v66, v66
	v_rcp_f32_e32 v67, v67
	v_rcp_f32_e32 v72, v72
	v_rcp_f32_e32 v73, v73
	s_waitcnt lgkmcnt(0)
	v_lshlrev_b32_e32 v103, 16, v75
	v_lshlrev_b32_e32 v102, 16, v74
	v_pk_mul_f32 v[66:67], v[66:67], v[102:103]
	v_pk_mul_f32 v[68:69], v[72:73], v[68:69]
	v_and_b32_e32 v99, 0xffff0000, v129
	v_pk_mul_f32 v[66:67], v[68:69], v[66:67]
	v_and_b32_e32 v69, 0xffff0000, v75
	v_and_b32_e32 v68, 0xffff0000, v74
	v_pk_mul_f32 v[68:69], v[70:71], v[68:69]
	v_mul_f32_e32 v70, 0xbfb8aa3b, v99
	v_exp_f32_e32 v70, v70
	v_or3_b32 v1, v1, s88, 48
	v_and_b32_e32 v72, 0xffff0000, v126
	v_and_b32_e32 v73, 0xffff0000, v127
	v_add_f32_e32 v70, 1.0, v70
	v_rcp_f32_e32 v101, v70
	v_readlane_b32 s10, v255, 3
	v_readlane_b32 s11, v255, 4
	v_pk_mul_f32 v[70:71], v[100:101], v[98:99]
	s_nop 0
	v_pk_mul_f32 v[68:69], v[70:71], v[68:69]
	s_nop 0
	v_cvt_pk_bf16_f32 v69, v67, v69
	v_cvt_pk_bf16_f32 v68, v66, v68
	v_mad_i64_i32 v[66:67], s[0:1], v1, s4, v[92:93]
	v_add_f32_e32 v1, v46, v62
	v_mul_f32_e32 v1, 0xbfb8aa3b, v1
	v_exp_f32_e32 v1, v1
	v_lshl_add_u64 v[66:67], v[66:67], 0, v[90:91]
	global_store_dwordx2 v[66:67], v[68:69], off offset:2560
	v_lshlrev_b32_e32 v91, 16, v79
	v_add_f32_e32 v1, 1.0, v1
	v_rcp_f32_e32 v62, v1
	v_add_f32_e32 v1, v47, v63
	v_mul_f32_e32 v1, 0xbfb8aa3b, v1
	v_exp_f32_e32 v1, v1
	v_lshlrev_b32_e32 v90, 16, v78
	v_add_f32_e32 v1, 1.0, v1
	v_rcp_f32_e32 v68, v1
	v_add_f32_e32 v1, v48, v64
	v_mul_f32_e32 v1, 0xbfb8aa3b, v1
	v_exp_f32_e32 v1, v1
	v_lshlrev_b32_e32 v64, 16, v126
	v_add_f32_e32 v1, 1.0, v1
	v_rcp_f32_e32 v63, v1
	v_add_f32_e32 v1, v49, v65
	v_mul_f32_e32 v1, 0xbfb8aa3b, v1
	v_exp_f32_e32 v1, v1
	v_lshlrev_b32_e32 v65, 16, v127
	v_pk_mul_f32 v[62:63], v[62:63], v[90:91]
	v_add_f32_e32 v1, 1.0, v1
	v_rcp_f32_e32 v69, v1
	v_mul_f32_e32 v1, 0xbfb8aa3b, v64
	v_exp_f32_e32 v1, v1
	s_nop 0
	v_add_f32_e32 v1, 1.0, v1
	v_rcp_f32_e32 v70, v1
	v_mul_f32_e32 v1, 0xbfb8aa3b, v72
	v_exp_f32_e32 v1, v1
	s_nop 0
	v_add_f32_e32 v1, 1.0, v1
	v_rcp_f32_e32 v74, v1
	v_mul_f32_e32 v1, 0xbfb8aa3b, v65
	v_exp_f32_e32 v1, v1
	s_nop 0
	v_add_f32_e32 v1, 1.0, v1
	v_rcp_f32_e32 v71, v1
	v_mul_f32_e32 v1, 0xbfb8aa3b, v73
	v_exp_f32_e32 v1, v1
	v_pk_mul_f32 v[64:65], v[70:71], v[64:65]
	s_nop 0
	v_pk_mul_f32 v[62:63], v[64:65], v[62:63]
	v_add_f32_e32 v1, 1.0, v1
	v_rcp_f32_e32 v75, v1
	v_and_b32_e32 v65, 0xffff0000, v79
	v_and_b32_e32 v64, 0xffff0000, v78
	v_pk_mul_f32 v[64:65], v[68:69], v[64:65]
	v_pk_mul_f32 v[68:69], v[74:75], v[72:73]
	s_nop 0
	v_pk_mul_f32 v[64:65], v[68:69], v[64:65]
	s_nop 0
	v_cvt_pk_bf16_f32 v63, v63, v65
	v_add_f32_e32 v1, v46, v58
	v_mul_f32_e32 v1, 0xbfb8aa3b, v1
	v_exp_f32_e32 v1, v1
	v_cvt_pk_bf16_f32 v62, v62, v64
	v_add_f32_e32 v1, 1.0, v1
	v_rcp_f32_e32 v58, v1
	v_add_f32_e32 v1, v47, v59
	v_mul_f32_e32 v1, 0xbfb8aa3b, v1
	v_exp_f32_e32 v1, v1
	s_nop 0
	v_add_f32_e32 v1, 1.0, v1
	global_store_dwordx2 v[88:89], v[62:63], off offset:2592
	v_rcp_f32_e32 v62, v1
	v_add_f32_e32 v1, v48, v60
	v_mul_f32_e32 v1, 0xbfb8aa3b, v1
	v_exp_f32_e32 v1, v1
	v_lshlrev_b32_e32 v60, 16, v124
	v_and_b32_e32 v68, 0xffff0000, v124
	v_and_b32_e32 v69, 0xffff0000, v125
	v_add_f32_e32 v1, 1.0, v1
	v_rcp_f32_e32 v59, v1
	v_add_f32_e32 v1, v49, v61
	v_mul_f32_e32 v1, 0xbfb8aa3b, v1
	v_exp_f32_e32 v1, v1
	v_lshlrev_b32_e32 v61, 16, v125
	v_lshlrev_b32_e32 v73, 16, v83
	v_lshlrev_b32_e32 v72, 16, v82
	v_add_f32_e32 v1, 1.0, v1
	v_rcp_f32_e32 v63, v1
	v_mul_f32_e32 v1, 0xbfb8aa3b, v60
	v_exp_f32_e32 v1, v1
	v_pk_mul_f32 v[58:59], v[58:59], v[72:73]
	v_add_f32_e32 v1, 1.0, v1
	v_rcp_f32_e32 v64, v1
	v_mul_f32_e32 v1, 0xbfb8aa3b, v68
	v_exp_f32_e32 v1, v1
	s_nop 0
	v_add_f32_e32 v1, 1.0, v1
	v_rcp_f32_e32 v70, v1
	v_mul_f32_e32 v1, 0xbfb8aa3b, v61
	v_exp_f32_e32 v1, v1
	s_nop 0
	v_add_f32_e32 v1, 1.0, v1
	v_rcp_f32_e32 v65, v1
	v_mul_f32_e32 v1, 0xbfb8aa3b, v69
	v_exp_f32_e32 v1, v1
	v_pk_mul_f32 v[60:61], v[64:65], v[60:61]
	s_nop 0
	v_pk_mul_f32 v[58:59], v[60:61], v[58:59]
	v_add_f32_e32 v1, 1.0, v1
	v_rcp_f32_e32 v71, v1
	v_and_b32_e32 v61, 0xffff0000, v83
	v_and_b32_e32 v60, 0xffff0000, v82
	v_pk_mul_f32 v[60:61], v[62:63], v[60:61]
	v_pk_mul_f32 v[62:63], v[70:71], v[68:69]
	s_nop 0
	v_pk_mul_f32 v[60:61], v[62:63], v[60:61]
	s_nop 0
	v_cvt_pk_bf16_f32 v59, v59, v61
	v_add_f32_e32 v1, v46, v54
	v_mul_f32_e32 v1, 0xbfb8aa3b, v1
	v_exp_f32_e32 v1, v1
	v_cvt_pk_bf16_f32 v58, v58, v60
	v_add_f32_e32 v1, 1.0, v1
	v_rcp_f32_e32 v54, v1
	v_add_f32_e32 v1, v47, v55
	v_mul_f32_e32 v1, 0xbfb8aa3b, v1
	v_exp_f32_e32 v1, v1
	s_nop 0
	v_add_f32_e32 v1, 1.0, v1
	global_store_dwordx2 v[80:81], v[58:59], off offset:2592
	v_rcp_f32_e32 v58, v1
	v_add_f32_e32 v1, v48, v56
	v_mul_f32_e32 v1, 0xbfb8aa3b, v1
	v_exp_f32_e32 v1, v1
	v_lshlrev_b32_e32 v56, 16, v122
	v_and_b32_e32 v62, 0xffff0000, v122
	v_and_b32_e32 v63, 0xffff0000, v123
	v_add_f32_e32 v1, 1.0, v1
	v_rcp_f32_e32 v55, v1
	v_add_f32_e32 v1, v49, v57
	v_mul_f32_e32 v1, 0xbfb8aa3b, v1
	v_exp_f32_e32 v1, v1
	v_lshlrev_b32_e32 v57, 16, v123
	v_lshlrev_b32_e32 v69, 16, v87
	v_lshlrev_b32_e32 v68, 16, v86
	v_add_f32_e32 v1, 1.0, v1
	v_rcp_f32_e32 v59, v1
	v_mul_f32_e32 v1, 0xbfb8aa3b, v56
	v_exp_f32_e32 v1, v1
	v_pk_mul_f32 v[54:55], v[54:55], v[68:69]
	v_add_f32_e32 v1, 1.0, v1
	v_rcp_f32_e32 v60, v1
	v_mul_f32_e32 v1, 0xbfb8aa3b, v62
	v_exp_f32_e32 v1, v1
	s_nop 0
	v_add_f32_e32 v1, 1.0, v1
	v_rcp_f32_e32 v64, v1
	v_mul_f32_e32 v1, 0xbfb8aa3b, v57
	v_exp_f32_e32 v1, v1
	s_nop 0
	v_add_f32_e32 v1, 1.0, v1
	v_rcp_f32_e32 v61, v1
	v_mul_f32_e32 v1, 0xbfb8aa3b, v63
	v_exp_f32_e32 v1, v1
	v_pk_mul_f32 v[56:57], v[60:61], v[56:57]
	s_nop 0
	v_pk_mul_f32 v[54:55], v[56:57], v[54:55]
	v_add_f32_e32 v1, 1.0, v1
	v_rcp_f32_e32 v65, v1
	v_and_b32_e32 v57, 0xffff0000, v87
	v_and_b32_e32 v56, 0xffff0000, v86
	v_pk_mul_f32 v[56:57], v[58:59], v[56:57]
	v_pk_mul_f32 v[58:59], v[64:65], v[62:63]
	s_nop 0
	v_pk_mul_f32 v[56:57], v[58:59], v[56:57]
	s_nop 0
	v_cvt_pk_bf16_f32 v55, v55, v57
	v_add_f32_e32 v1, v46, v50
	v_mul_f32_e32 v1, 0xbfb8aa3b, v1
	v_exp_f32_e32 v1, v1
	v_cvt_pk_bf16_f32 v54, v54, v56
	v_add_f32_e32 v1, 1.0, v1
	v_rcp_f32_e32 v46, v1
	v_add_f32_e32 v1, v47, v51
	v_mul_f32_e32 v1, 0xbfb8aa3b, v1
	v_exp_f32_e32 v1, v1
	s_nop 0
	v_add_f32_e32 v1, 1.0, v1
	v_rcp_f32_e32 v50, v1
	v_add_f32_e32 v1, v48, v52
	v_mul_f32_e32 v1, 0xbfb8aa3b, v1
	v_exp_f32_e32 v1, v1
	v_lshlrev_b32_e32 v48, 16, v120
	global_store_dwordx2 v[84:85], v[54:55], off offset:2592
	v_and_b32_e32 v54, 0xffff0000, v120
	v_add_f32_e32 v1, 1.0, v1
	v_rcp_f32_e32 v47, v1
	v_add_f32_e32 v1, v49, v53
	v_mul_f32_e32 v1, 0xbfb8aa3b, v1
	v_exp_f32_e32 v1, v1
	v_lshlrev_b32_e32 v49, 16, v121
	v_and_b32_e32 v55, 0xffff0000, v121
	v_lshlrev_b32_e32 v59, 16, v77
	v_add_f32_e32 v1, 1.0, v1
	v_rcp_f32_e32 v51, v1
	v_mul_f32_e32 v1, 0xbfb8aa3b, v48
	v_exp_f32_e32 v1, v1
	v_lshlrev_b32_e32 v58, 16, v76
	v_pk_mul_f32 v[46:47], v[46:47], v[58:59]
	v_add_f32_e32 v1, 1.0, v1
	v_rcp_f32_e32 v52, v1
	v_mul_f32_e32 v1, 0xbfb8aa3b, v54
	v_exp_f32_e32 v1, v1
	s_nop 0
	v_add_f32_e32 v1, 1.0, v1
	v_rcp_f32_e32 v56, v1
	v_mul_f32_e32 v1, 0xbfb8aa3b, v49
	v_exp_f32_e32 v1, v1
	s_nop 0
	v_add_f32_e32 v1, 1.0, v1
	v_rcp_f32_e32 v53, v1
	v_mul_f32_e32 v1, 0xbfb8aa3b, v55
	v_exp_f32_e32 v1, v1
	v_pk_mul_f32 v[48:49], v[52:53], v[48:49]
	s_nop 0
	v_pk_mul_f32 v[46:47], v[48:49], v[46:47]
	v_add_f32_e32 v1, 1.0, v1
	v_rcp_f32_e32 v57, v1
	v_and_b32_e32 v49, 0xffff0000, v77
	v_and_b32_e32 v48, 0xffff0000, v76
	v_pk_mul_f32 v[48:49], v[50:51], v[48:49]
	v_pk_mul_f32 v[50:51], v[56:57], v[54:55]
	s_nop 0
	v_pk_mul_f32 v[48:49], v[50:51], v[48:49]
	s_nop 0
	v_cvt_pk_bf16_f32 v47, v47, v49
	v_add_f32_e32 v1, v26, v42
	v_mul_f32_e32 v1, 0xbfb8aa3b, v1
	v_exp_f32_e32 v1, v1
	v_cvt_pk_bf16_f32 v46, v46, v48
	v_add_f32_e32 v1, 1.0, v1
	v_rcp_f32_e32 v42, v1
	v_add_f32_e32 v1, v27, v43
	v_mul_f32_e32 v1, 0xbfb8aa3b, v1
	v_exp_f32_e32 v1, v1
	v_and_b32_e32 v54, 0xffff0000, v118
	v_and_b32_e32 v55, 0xffff0000, v119
	v_add_f32_e32 v1, 1.0, v1
	v_rcp_f32_e32 v50, v1
	v_add_f32_e32 v1, v28, v44
	v_mul_f32_e32 v1, 0xbfb8aa3b, v1
	v_exp_f32_e32 v1, v1
	v_lshlrev_b32_e32 v44, 16, v118
	v_add_f32_e32 v1, 1.0, v1
	v_rcp_f32_e32 v43, v1
	v_add_f32_e32 v1, v29, v45
	v_mul_f32_e32 v1, 0xbfb8aa3b, v1
	v_exp_f32_e32 v1, v1
	v_lshlrev_b32_e32 v45, 16, v119
	global_store_dwordx2 v[66:67], v[46:47], off offset:2592
	ds_read2_b64 v[46:49], v97 offset0:40 offset1:44
	v_add_f32_e32 v1, 1.0, v1
	v_rcp_f32_e32 v51, v1
	v_mul_f32_e32 v1, 0xbfb8aa3b, v44
	v_exp_f32_e32 v1, v1
	s_waitcnt lgkmcnt(0)
	v_lshlrev_b32_e32 v59, 16, v47
	v_lshlrev_b32_e32 v58, 16, v46
	v_pk_mul_f32 v[42:43], v[42:43], v[58:59]
	v_add_f32_e32 v1, 1.0, v1
	v_rcp_f32_e32 v52, v1
	v_mul_f32_e32 v1, 0xbfb8aa3b, v54
	v_exp_f32_e32 v1, v1
	s_nop 0
	v_add_f32_e32 v1, 1.0, v1
	v_rcp_f32_e32 v56, v1
	v_mul_f32_e32 v1, 0xbfb8aa3b, v45
	v_exp_f32_e32 v1, v1
	s_nop 0
	v_add_f32_e32 v1, 1.0, v1
	v_rcp_f32_e32 v53, v1
	v_mul_f32_e32 v1, 0xbfb8aa3b, v55
	v_exp_f32_e32 v1, v1
	v_pk_mul_f32 v[44:45], v[52:53], v[44:45]
	s_nop 0
	v_pk_mul_f32 v[42:43], v[44:45], v[42:43]
	v_add_f32_e32 v1, 1.0, v1
	v_rcp_f32_e32 v57, v1
	v_and_b32_e32 v45, 0xffff0000, v47
	v_and_b32_e32 v44, 0xffff0000, v46
	v_pk_mul_f32 v[44:45], v[50:51], v[44:45]
	v_pk_mul_f32 v[46:47], v[56:57], v[54:55]
	s_nop 0
	v_pk_mul_f32 v[44:45], v[46:47], v[44:45]
	s_nop 0
	v_cvt_pk_bf16_f32 v43, v43, v45
	v_add_f32_e32 v1, v26, v38
	v_mul_f32_e32 v1, 0xbfb8aa3b, v1
	v_exp_f32_e32 v1, v1
	v_cvt_pk_bf16_f32 v42, v42, v44
	v_add_f32_e32 v1, 1.0, v1
	global_store_dwordx2 v[88:89], v[42:43], off offset:2624
	v_rcp_f32_e32 v42, v1
	v_add_f32_e32 v1, v27, v39
	v_mul_f32_e32 v1, 0xbfb8aa3b, v1
	v_exp_f32_e32 v1, v1
	v_lshlrev_b32_e32 v46, 16, v116
	v_and_b32_e32 v52, 0xffff0000, v116
	v_lshlrev_b32_e32 v47, 16, v117
	v_add_f32_e32 v1, 1.0, v1
	v_rcp_f32_e32 v44, v1
	v_add_f32_e32 v1, v28, v40
	v_mul_f32_e32 v1, 0xbfb8aa3b, v1
	v_exp_f32_e32 v1, v1
	v_and_b32_e32 v53, 0xffff0000, v117
	v_add_f32_e32 v1, 1.0, v1
	v_rcp_f32_e32 v43, v1
	v_add_f32_e32 v1, v29, v41
	v_mul_f32_e32 v1, 0xbfb8aa3b, v1
	v_exp_f32_e32 v1, v1
	ds_read2_b64 v[38:41], v94 offset0:40 offset1:44
	v_add_f32_e32 v1, 1.0, v1
	v_rcp_f32_e32 v45, v1
	v_mul_f32_e32 v1, 0xbfb8aa3b, v46
	v_exp_f32_e32 v1, v1
	s_waitcnt lgkmcnt(0)
	v_lshlrev_b32_e32 v57, 16, v39
	v_lshlrev_b32_e32 v56, 16, v38
	v_pk_mul_f32 v[42:43], v[42:43], v[56:57]
	v_add_f32_e32 v1, 1.0, v1
	v_rcp_f32_e32 v50, v1
	v_mul_f32_e32 v1, 0xbfb8aa3b, v52
	v_exp_f32_e32 v1, v1
	v_and_b32_e32 v39, 0xffff0000, v39
	v_and_b32_e32 v38, 0xffff0000, v38
	v_pk_mul_f32 v[38:39], v[44:45], v[38:39]
	v_add_f32_e32 v1, 1.0, v1
	v_rcp_f32_e32 v54, v1
	v_mul_f32_e32 v1, 0xbfb8aa3b, v47
	v_exp_f32_e32 v1, v1
	s_nop 0
	v_add_f32_e32 v1, 1.0, v1
	v_rcp_f32_e32 v51, v1
	v_mul_f32_e32 v1, 0xbfb8aa3b, v53
	v_exp_f32_e32 v1, v1
	v_pk_mul_f32 v[46:47], v[50:51], v[46:47]
	s_nop 0
	v_pk_mul_f32 v[42:43], v[46:47], v[42:43]
	v_add_f32_e32 v1, 1.0, v1
	v_rcp_f32_e32 v55, v1
	v_and_b32_e32 v50, 0xffff0000, v114
	v_pk_mul_f32 v[44:45], v[54:55], v[52:53]
	v_and_b32_e32 v51, 0xffff0000, v115
	v_pk_mul_f32 v[38:39], v[44:45], v[38:39]
	s_nop 0
	v_cvt_pk_bf16_f32 v39, v43, v39
	v_add_f32_e32 v1, v26, v34
	v_mul_f32_e32 v1, 0xbfb8aa3b, v1
	v_exp_f32_e32 v1, v1
	v_cvt_pk_bf16_f32 v42, v42, v42
	v_cvt_pk_bf16_f32 v38, v38, v38
	v_add_f32_e32 v1, 1.0, v1
	v_rcp_f32_e32 v34, v1
	v_add_f32_e32 v1, v27, v35
	v_mul_f32_e32 v1, 0xbfb8aa3b, v1
	v_exp_f32_e32 v1, v1
	v_bfi_b32 v38, s33, v38, v42
	v_lshlrev_b32_e32 v44, 16, v114
	v_add_f32_e32 v1, 1.0, v1
	v_rcp_f32_e32 v42, v1
	v_add_f32_e32 v1, v28, v36
	v_mul_f32_e32 v1, 0xbfb8aa3b, v1
	v_exp_f32_e32 v1, v1
	v_lshlrev_b32_e32 v45, 16, v115
	global_store_dwordx2 v[80:81], v[38:39], off offset:2624
	v_add_f32_e32 v1, 1.0, v1
	v_rcp_f32_e32 v35, v1
	v_add_f32_e32 v1, v29, v37
	v_mul_f32_e32 v1, 0xbfb8aa3b, v1
	v_exp_f32_e32 v1, v1
	ds_read2_b64 v[36:39], v95 offset0:40 offset1:44
	v_add_f32_e32 v1, 1.0, v1
	v_rcp_f32_e32 v43, v1
	v_mul_f32_e32 v1, 0xbfb8aa3b, v44
	v_exp_f32_e32 v1, v1
	s_waitcnt lgkmcnt(0)
	v_lshlrev_b32_e32 v55, 16, v37
	v_lshlrev_b32_e32 v54, 16, v36
	v_pk_mul_f32 v[34:35], v[34:35], v[54:55]
	v_add_f32_e32 v1, 1.0, v1
	v_rcp_f32_e32 v46, v1
	v_mul_f32_e32 v1, 0xbfb8aa3b, v50
	v_exp_f32_e32 v1, v1
	v_and_b32_e32 v37, 0xffff0000, v37
	v_and_b32_e32 v36, 0xffff0000, v36
	v_pk_mul_f32 v[36:37], v[42:43], v[36:37]
	v_add_f32_e32 v1, 1.0, v1
	v_rcp_f32_e32 v52, v1
	v_mul_f32_e32 v1, 0xbfb8aa3b, v45
	v_exp_f32_e32 v1, v1
	s_nop 0
	v_add_f32_e32 v1, 1.0, v1
	v_rcp_f32_e32 v47, v1
	v_mul_f32_e32 v1, 0xbfb8aa3b, v51
	v_exp_f32_e32 v1, v1
	v_pk_mul_f32 v[44:45], v[46:47], v[44:45]
	s_nop 0
	v_pk_mul_f32 v[34:35], v[44:45], v[34:35]
	v_add_f32_e32 v1, 1.0, v1
	v_rcp_f32_e32 v53, v1
	s_nop 0
	v_pk_mul_f32 v[42:43], v[52:53], v[50:51]
	s_nop 0
	v_pk_mul_f32 v[36:37], v[42:43], v[36:37]
	s_nop 0
	v_cvt_pk_bf16_f32 v35, v35, v37
	v_add_f32_e32 v1, v26, v30
	v_mul_f32_e32 v1, 0xbfb8aa3b, v1
	v_exp_f32_e32 v1, v1
	v_cvt_pk_bf16_f32 v34, v34, v34
	v_cvt_pk_bf16_f32 v36, v36, v36
	v_add_f32_e32 v1, 1.0, v1
	v_rcp_f32_e32 v26, v1
	v_add_f32_e32 v1, v27, v31
	v_mul_f32_e32 v1, 0xbfb8aa3b, v1
	v_exp_f32_e32 v1, v1
	v_and_b32_e32 v42, 0xffff0000, v112
	v_and_b32_e32 v43, 0xffff0000, v113
	v_add_f32_e32 v1, 1.0, v1
	v_rcp_f32_e32 v30, v1
	v_add_f32_e32 v1, v28, v32
	v_mul_f32_e32 v1, 0xbfb8aa3b, v1
	v_exp_f32_e32 v1, v1
	v_lshlrev_b32_e32 v28, 16, v112
	v_bfi_b32 v34, s33, v36, v34
	global_store_dwordx2 v[84:85], v[34:35], off offset:2624
	v_add_f32_e32 v1, 1.0, v1
	v_rcp_f32_e32 v27, v1
	v_add_f32_e32 v1, v29, v33
	v_mul_f32_e32 v1, 0xbfb8aa3b, v1
	v_exp_f32_e32 v1, v1
	v_lshlrev_b32_e32 v29, 16, v113
	ds_read2_b64 v[34:37], v96 offset0:72 offset1:76
	v_add_f32_e32 v1, 1.0, v1
	v_rcp_f32_e32 v31, v1
	v_mul_f32_e32 v1, 0xbfb8aa3b, v28
	v_exp_f32_e32 v1, v1
	s_waitcnt lgkmcnt(0)
	v_lshlrev_b32_e32 v47, 16, v35
	v_lshlrev_b32_e32 v46, 16, v34
	v_pk_mul_f32 v[26:27], v[26:27], v[46:47]
	v_add_f32_e32 v1, 1.0, v1
	v_rcp_f32_e32 v32, v1
	v_mul_f32_e32 v1, 0xbfb8aa3b, v42
	v_exp_f32_e32 v1, v1
	s_nop 0
	v_add_f32_e32 v1, 1.0, v1
	v_rcp_f32_e32 v44, v1
	v_mul_f32_e32 v1, 0xbfb8aa3b, v29
	v_exp_f32_e32 v1, v1
	s_nop 0
	v_add_f32_e32 v1, 1.0, v1
	v_rcp_f32_e32 v33, v1
	v_mul_f32_e32 v1, 0xbfb8aa3b, v43
	v_exp_f32_e32 v1, v1
	v_pk_mul_f32 v[28:29], v[32:33], v[28:29]
	s_nop 0
	v_pk_mul_f32 v[26:27], v[28:29], v[26:27]
	v_add_f32_e32 v1, 1.0, v1
	v_rcp_f32_e32 v45, v1
	v_and_b32_e32 v29, 0xffff0000, v35
	v_and_b32_e32 v28, 0xffff0000, v34
	v_pk_mul_f32 v[28:29], v[30:31], v[28:29]
	v_pk_mul_f32 v[30:31], v[44:45], v[42:43]
	s_nop 0
	v_pk_mul_f32 v[28:29], v[30:31], v[28:29]
	s_nop 0
	v_cvt_pk_bf16_f32 v27, v27, v29
	v_add_f32_e32 v1, v6, v22
	v_mul_f32_e32 v1, 0xbfb8aa3b, v1
	v_exp_f32_e32 v1, v1
	v_cvt_pk_bf16_f32 v26, v26, v28
	v_add_f32_e32 v1, 1.0, v1
	v_rcp_f32_e32 v22, v1
	v_add_f32_e32 v1, v7, v23
	v_mul_f32_e32 v1, 0xbfb8aa3b, v1
	v_exp_f32_e32 v1, v1
	s_nop 0
	v_add_f32_e32 v1, 1.0, v1
	global_store_dwordx2 v[66:67], v[26:27], off offset:2624
	v_rcp_f32_e32 v26, v1
	v_add_f32_e32 v1, v8, v24
	v_mul_f32_e32 v1, 0xbfb8aa3b, v1
	v_exp_f32_e32 v1, v1
	v_lshlrev_b32_e32 v24, 16, v110
	v_and_b32_e32 v30, 0xffff0000, v110
	v_and_b32_e32 v31, 0xffff0000, v111
	v_add_f32_e32 v1, 1.0, v1
	v_rcp_f32_e32 v23, v1
	v_add_f32_e32 v1, v9, v25
	v_mul_f32_e32 v1, 0xbfb8aa3b, v1
	v_exp_f32_e32 v1, v1
	v_lshlrev_b32_e32 v25, 16, v111
	v_lshlrev_b32_e32 v35, 16, v49
	v_lshlrev_b32_e32 v34, 16, v48
	v_add_f32_e32 v1, 1.0, v1
	v_rcp_f32_e32 v27, v1
	v_mul_f32_e32 v1, 0xbfb8aa3b, v24
	v_exp_f32_e32 v1, v1
	v_pk_mul_f32 v[22:23], v[22:23], v[34:35]
	v_add_f32_e32 v1, 1.0, v1
	v_rcp_f32_e32 v28, v1
	v_mul_f32_e32 v1, 0xbfb8aa3b, v30
	v_exp_f32_e32 v1, v1
	s_nop 0
	v_add_f32_e32 v1, 1.0, v1
	v_rcp_f32_e32 v32, v1
	v_mul_f32_e32 v1, 0xbfb8aa3b, v25
	v_exp_f32_e32 v1, v1
	s_nop 0
	v_add_f32_e32 v1, 1.0, v1
	v_rcp_f32_e32 v29, v1
	v_mul_f32_e32 v1, 0xbfb8aa3b, v31
	v_exp_f32_e32 v1, v1
	v_pk_mul_f32 v[24:25], v[28:29], v[24:25]
	s_nop 0
	v_pk_mul_f32 v[22:23], v[24:25], v[22:23]
	v_add_f32_e32 v1, 1.0, v1
	v_rcp_f32_e32 v33, v1
	v_and_b32_e32 v25, 0xffff0000, v49
	v_and_b32_e32 v24, 0xffff0000, v48
	v_pk_mul_f32 v[24:25], v[26:27], v[24:25]
	v_pk_mul_f32 v[26:27], v[32:33], v[30:31]
	s_nop 0
	v_pk_mul_f32 v[24:25], v[26:27], v[24:25]
	s_nop 0
	v_cvt_pk_bf16_f32 v23, v23, v25
	v_add_f32_e32 v1, v6, v18
	v_mul_f32_e32 v1, 0xbfb8aa3b, v1
	v_exp_f32_e32 v1, v1
	v_cvt_pk_bf16_f32 v22, v22, v24
	v_add_f32_e32 v1, 1.0, v1
	v_rcp_f32_e32 v18, v1
	v_add_f32_e32 v1, v7, v19
	v_mul_f32_e32 v1, 0xbfb8aa3b, v1
	v_exp_f32_e32 v1, v1
	s_nop 0
	v_add_f32_e32 v1, 1.0, v1
	global_store_dwordx2 v[88:89], v[22:23], off offset:2656
	v_rcp_f32_e32 v22, v1
	v_add_f32_e32 v1, v8, v20
	v_mul_f32_e32 v1, 0xbfb8aa3b, v1
	v_exp_f32_e32 v1, v1
	v_lshlrev_b32_e32 v20, 16, v108
	v_and_b32_e32 v26, 0xffff0000, v108
	v_and_b32_e32 v27, 0xffff0000, v109
	v_add_f32_e32 v1, 1.0, v1
	v_rcp_f32_e32 v19, v1
	v_add_f32_e32 v1, v9, v21
	v_mul_f32_e32 v1, 0xbfb8aa3b, v1
	v_exp_f32_e32 v1, v1
	v_lshlrev_b32_e32 v21, 16, v109
	v_lshlrev_b32_e32 v31, 16, v41
	v_lshlrev_b32_e32 v30, 16, v40
	v_add_f32_e32 v1, 1.0, v1
	v_rcp_f32_e32 v23, v1
	v_mul_f32_e32 v1, 0xbfb8aa3b, v20
	v_exp_f32_e32 v1, v1
	v_pk_mul_f32 v[18:19], v[18:19], v[30:31]
	v_add_f32_e32 v1, 1.0, v1
	v_rcp_f32_e32 v24, v1
	v_mul_f32_e32 v1, 0xbfb8aa3b, v26
	v_exp_f32_e32 v1, v1
	s_nop 0
	v_add_f32_e32 v1, 1.0, v1
	v_rcp_f32_e32 v28, v1
	v_mul_f32_e32 v1, 0xbfb8aa3b, v21
	v_exp_f32_e32 v1, v1
	s_nop 0
	v_add_f32_e32 v1, 1.0, v1
	v_rcp_f32_e32 v25, v1
	v_mul_f32_e32 v1, 0xbfb8aa3b, v27
	v_exp_f32_e32 v1, v1
	v_pk_mul_f32 v[20:21], v[24:25], v[20:21]
	s_nop 0
	v_pk_mul_f32 v[18:19], v[20:21], v[18:19]
	v_add_f32_e32 v1, 1.0, v1
	v_rcp_f32_e32 v29, v1
	v_and_b32_e32 v21, 0xffff0000, v41
	v_and_b32_e32 v20, 0xffff0000, v40
	v_pk_mul_f32 v[20:21], v[22:23], v[20:21]
	v_pk_mul_f32 v[22:23], v[28:29], v[26:27]
	s_nop 0
	v_pk_mul_f32 v[20:21], v[22:23], v[20:21]
	s_nop 0
	v_cvt_pk_bf16_f32 v19, v19, v21
	v_add_f32_e32 v1, v6, v14
	v_mul_f32_e32 v1, 0xbfb8aa3b, v1
	v_exp_f32_e32 v1, v1
	v_cvt_pk_bf16_f32 v18, v18, v20
	v_add_f32_e32 v1, 1.0, v1
	v_rcp_f32_e32 v14, v1
	v_add_f32_e32 v1, v7, v15
	v_mul_f32_e32 v1, 0xbfb8aa3b, v1
	v_exp_f32_e32 v1, v1
	s_nop 0
	v_add_f32_e32 v1, 1.0, v1
	global_store_dwordx2 v[80:81], v[18:19], off offset:2656
	v_rcp_f32_e32 v18, v1
	v_add_f32_e32 v1, v8, v16
	v_mul_f32_e32 v1, 0xbfb8aa3b, v1
	v_exp_f32_e32 v1, v1
	v_lshlrev_b32_e32 v16, 16, v106
	v_and_b32_e32 v22, 0xffff0000, v106
	v_and_b32_e32 v23, 0xffff0000, v107
	v_add_f32_e32 v1, 1.0, v1
	v_rcp_f32_e32 v15, v1
	v_add_f32_e32 v1, v9, v17
	v_mul_f32_e32 v1, 0xbfb8aa3b, v1
	v_exp_f32_e32 v1, v1
	v_lshlrev_b32_e32 v17, 16, v107
	v_lshlrev_b32_e32 v27, 16, v39
	v_lshlrev_b32_e32 v26, 16, v38
	v_add_f32_e32 v1, 1.0, v1
	v_rcp_f32_e32 v19, v1
	v_mul_f32_e32 v1, 0xbfb8aa3b, v16
	v_exp_f32_e32 v1, v1
	v_pk_mul_f32 v[14:15], v[14:15], v[26:27]
	v_add_f32_e32 v1, 1.0, v1
	v_rcp_f32_e32 v20, v1
	v_mul_f32_e32 v1, 0xbfb8aa3b, v22
	v_exp_f32_e32 v1, v1
	s_nop 0
	v_add_f32_e32 v1, 1.0, v1
	v_rcp_f32_e32 v24, v1
	v_mul_f32_e32 v1, 0xbfb8aa3b, v17
	v_exp_f32_e32 v1, v1
	s_nop 0
	v_add_f32_e32 v1, 1.0, v1
	v_rcp_f32_e32 v21, v1
	v_mul_f32_e32 v1, 0xbfb8aa3b, v23
	v_exp_f32_e32 v1, v1
	v_pk_mul_f32 v[16:17], v[20:21], v[16:17]
	s_nop 0
	v_pk_mul_f32 v[14:15], v[16:17], v[14:15]
	v_add_f32_e32 v1, 1.0, v1
	v_rcp_f32_e32 v25, v1
	v_and_b32_e32 v17, 0xffff0000, v39
	v_and_b32_e32 v16, 0xffff0000, v38
	v_pk_mul_f32 v[16:17], v[18:19], v[16:17]
	v_pk_mul_f32 v[18:19], v[24:25], v[22:23]
	s_nop 0
	v_pk_mul_f32 v[16:17], v[18:19], v[16:17]
	s_nop 0
	v_cvt_pk_bf16_f32 v15, v15, v17
	v_add_f32_e32 v1, v6, v10
	v_mul_f32_e32 v1, 0xbfb8aa3b, v1
	v_exp_f32_e32 v1, v1
	v_cvt_pk_bf16_f32 v14, v14, v16
	v_add_f32_e32 v1, 1.0, v1
	v_rcp_f32_e32 v6, v1
	v_add_f32_e32 v1, v7, v11
	v_mul_f32_e32 v1, 0xbfb8aa3b, v1
	v_exp_f32_e32 v1, v1
	s_nop 0
	v_add_f32_e32 v1, 1.0, v1
	v_rcp_f32_e32 v10, v1
	v_add_f32_e32 v1, v8, v12
	v_mul_f32_e32 v1, 0xbfb8aa3b, v1
	v_exp_f32_e32 v1, v1
	v_lshlrev_b32_e32 v8, 16, v104
	global_store_dwordx2 v[84:85], v[14:15], off offset:2656
	v_and_b32_e32 v14, 0xffff0000, v104
	v_add_f32_e32 v1, 1.0, v1
	v_rcp_f32_e32 v7, v1
	v_add_f32_e32 v1, v9, v13
	v_mul_f32_e32 v1, 0xbfb8aa3b, v1
	v_exp_f32_e32 v1, v1
	v_lshlrev_b32_e32 v9, 16, v105
	v_and_b32_e32 v15, 0xffff0000, v105
	v_lshlrev_b32_e32 v19, 16, v37
	v_add_f32_e32 v1, 1.0, v1
	v_rcp_f32_e32 v11, v1
	v_mul_f32_e32 v1, 0xbfb8aa3b, v8
	v_exp_f32_e32 v1, v1
	v_lshlrev_b32_e32 v18, 16, v36
	v_pk_mul_f32 v[6:7], v[6:7], v[18:19]
	v_add_f32_e32 v1, 1.0, v1
	v_rcp_f32_e32 v12, v1
	v_mul_f32_e32 v1, 0xbfb8aa3b, v14
	v_exp_f32_e32 v1, v1
	s_nop 0
	v_add_f32_e32 v1, 1.0, v1
	v_rcp_f32_e32 v16, v1
	v_mul_f32_e32 v1, 0xbfb8aa3b, v9
	v_exp_f32_e32 v1, v1
	s_nop 0
	v_add_f32_e32 v1, 1.0, v1
	v_rcp_f32_e32 v13, v1
	v_mul_f32_e32 v1, 0xbfb8aa3b, v15
	v_exp_f32_e32 v1, v1
	v_pk_mul_f32 v[8:9], v[12:13], v[8:9]
	s_nop 0
	v_pk_mul_f32 v[6:7], v[8:9], v[6:7]
	v_add_f32_e32 v1, 1.0, v1
	v_rcp_f32_e32 v17, v1
	v_and_b32_e32 v9, 0xffff0000, v37
	v_and_b32_e32 v8, 0xffff0000, v36
	v_pk_mul_f32 v[8:9], v[10:11], v[8:9]
	v_pk_mul_f32 v[10:11], v[16:17], v[14:15]
	s_nop 0
	v_pk_mul_f32 v[8:9], v[10:11], v[8:9]
	s_nop 0
	v_cvt_pk_bf16_f32 v7, v7, v9
	v_cvt_pk_bf16_f32 v6, v6, v8
	global_store_dwordx2 v[66:67], v[6:7], off offset:2656
	s_barrier

.LBB0_715:
	v_add_co_u32_e32 v70, vcc, 0xb00000, v30
	s_nop 1
	v_addc_co_u32_e32 v71, vcc, 0, v31, vcc
	global_load_dwordx4 v[72:75], v[28:29], off
	global_load_dwordx4 v[76:79], v[70:71], off
	global_load_dwordx4 v[80:83], v[28:29], off offset:64
	global_load_dwordx4 v[84:87], v[70:71], off offset:64
	global_load_dwordx4 v[88:91], v[28:29], off offset:128
	global_load_dwordx4 v[92:95], v[70:71], off offset:128
	global_load_dwordx4 v[96:99], v[28:29], off offset:192
	global_load_dwordx4 v[100:103], v[70:71], off offset:192
	global_load_dwordx4 v[104:107], v[28:29], off offset:256
	global_load_dwordx4 v[108:111], v[70:71], off offset:256
	global_load_dwordx4 v[112:115], v[28:29], off offset:320
	global_load_dwordx4 v[116:119], v[70:71], off offset:320
	global_load_dwordx4 v[120:123], v[28:29], off offset:384
	global_load_dwordx4 v[124:127], v[70:71], off offset:384
	global_load_dwordx4 v[128:131], v[28:29], off offset:448
	global_load_dwordx4 v[132:135], v[70:71], off offset:448
	global_load_dwordx4 v[162:165], v[28:29], off offset:512
	global_load_dwordx4 v[166:169], v[70:71], off offset:512
	global_load_dwordx4 v[170:173], v[28:29], off offset:576
	global_load_dwordx4 v[174:177], v[70:71], off offset:576
	global_load_dwordx4 v[178:181], v[28:29], off offset:640
	global_load_dwordx4 v[182:185], v[70:71], off offset:640
	global_load_dwordx4 v[186:189], v[28:29], off offset:704
	global_load_dwordx4 v[190:193], v[70:71], off offset:704
	global_load_dwordx4 v[194:197], v[28:29], off offset:768
	global_load_dwordx4 v[198:201], v[70:71], off offset:768
	global_load_dwordx4 v[202:205], v[28:29], off offset:832
	global_load_dwordx4 v[206:209], v[70:71], off offset:832
	global_load_dwordx4 v[210:213], v[28:29], off offset:896
	global_load_dwordx4 v[214:217], v[70:71], off offset:896
	global_load_dwordx4 v[218:221], v[28:29], off offset:960
	global_load_dwordx4 v[236:239], v[70:71], off offset:960
	s_waitcnt vmcnt(30)
	v_mfma_f32_16x16x32_bf16 v[22:25], v[76:79], v[72:75], v[22:25]
	s_waitcnt vmcnt(28)
	v_mfma_f32_16x16x32_bf16 v[22:25], v[84:87], v[80:83], v[22:25]
	s_waitcnt vmcnt(26)
	v_mfma_f32_16x16x32_bf16 v[22:25], v[92:95], v[88:91], v[22:25]
	s_waitcnt vmcnt(24)
	v_mfma_f32_16x16x32_bf16 v[22:25], v[100:103], v[96:99], v[22:25]
	s_waitcnt vmcnt(22)
	v_mfma_f32_16x16x32_bf16 v[22:25], v[108:111], v[104:107], v[22:25]
	s_waitcnt vmcnt(20)
	v_mfma_f32_16x16x32_bf16 v[22:25], v[116:119], v[112:115], v[22:25]
	s_waitcnt vmcnt(18)
	v_mfma_f32_16x16x32_bf16 v[22:25], v[124:127], v[120:123], v[22:25]
	s_waitcnt vmcnt(16)
	v_mfma_f32_16x16x32_bf16 v[22:25], v[132:135], v[128:131], v[22:25]
	global_load_dwordx4 v[72:75], v[28:29], off offset:1024
	global_load_dwordx4 v[76:79], v[70:71], off offset:1024
	global_load_dwordx4 v[80:83], v[28:29], off offset:1088
	global_load_dwordx4 v[84:87], v[70:71], off offset:1088
	global_load_dwordx4 v[88:91], v[28:29], off offset:1152
	global_load_dwordx4 v[92:95], v[70:71], off offset:1152
	global_load_dwordx4 v[96:99], v[28:29], off offset:1216
	global_load_dwordx4 v[100:103], v[70:71], off offset:1216
	global_load_dwordx4 v[104:107], v[28:29], off offset:1280
	global_load_dwordx4 v[108:111], v[70:71], off offset:1280
	global_load_dwordx4 v[112:115], v[28:29], off offset:1344
	global_load_dwordx4 v[116:119], v[70:71], off offset:1344
	global_load_dwordx4 v[120:123], v[28:29], off offset:1408
	global_load_dwordx4 v[124:127], v[70:71], off offset:1408
	global_load_dwordx4 v[128:131], v[28:29], off offset:1472
	global_load_dwordx4 v[132:135], v[70:71], off offset:1472
	s_waitcnt vmcnt(30)
	v_mfma_f32_16x16x32_bf16 v[22:25], v[166:169], v[162:165], v[22:25]
	s_waitcnt vmcnt(28)
	v_mfma_f32_16x16x32_bf16 v[22:25], v[174:177], v[170:173], v[22:25]
	s_waitcnt vmcnt(26)
	v_mfma_f32_16x16x32_bf16 v[22:25], v[182:185], v[178:181], v[22:25]
	s_waitcnt vmcnt(24)
	v_mfma_f32_16x16x32_bf16 v[22:25], v[190:193], v[186:189], v[22:25]
	s_waitcnt vmcnt(22)
	v_mfma_f32_16x16x32_bf16 v[22:25], v[198:201], v[194:197], v[22:25]
	s_waitcnt vmcnt(20)
	v_mfma_f32_16x16x32_bf16 v[22:25], v[206:209], v[202:205], v[22:25]
	s_waitcnt vmcnt(18)
	v_mfma_f32_16x16x32_bf16 v[22:25], v[214:217], v[210:213], v[22:25]
	s_waitcnt vmcnt(16)
	v_mfma_f32_16x16x32_bf16 v[22:25], v[236:239], v[218:221], v[22:25]
	global_load_dwordx4 v[162:165], v[28:29], off offset:1536
	global_load_dwordx4 v[166:169], v[70:71], off offset:1536
	global_load_dwordx4 v[170:173], v[28:29], off offset:1600
	global_load_dwordx4 v[174:177], v[70:71], off offset:1600
	global_load_dwordx4 v[178:181], v[28:29], off offset:1664
	global_load_dwordx4 v[182:185], v[70:71], off offset:1664
	global_load_dwordx4 v[186:189], v[28:29], off offset:1728
	global_load_dwordx4 v[190:193], v[70:71], off offset:1728
	global_load_dwordx4 v[194:197], v[28:29], off offset:1792
	global_load_dwordx4 v[198:201], v[70:71], off offset:1792
	global_load_dwordx4 v[202:205], v[28:29], off offset:1856
	global_load_dwordx4 v[206:209], v[70:71], off offset:1856
	global_load_dwordx4 v[210:213], v[28:29], off offset:1920
	global_load_dwordx4 v[214:217], v[70:71], off offset:1920
	global_load_dwordx4 v[218:221], v[28:29], off offset:1984
	global_load_dwordx4 v[236:239], v[70:71], off offset:1984
	s_waitcnt vmcnt(30)
	v_mfma_f32_16x16x32_bf16 v[22:25], v[76:79], v[72:75], v[22:25]
	s_waitcnt vmcnt(28)
	v_mfma_f32_16x16x32_bf16 v[22:25], v[84:87], v[80:83], v[22:25]
	s_waitcnt vmcnt(26)
	v_mfma_f32_16x16x32_bf16 v[22:25], v[92:95], v[88:91], v[22:25]
	s_waitcnt vmcnt(24)
	v_mfma_f32_16x16x32_bf16 v[22:25], v[100:103], v[96:99], v[22:25]
	s_waitcnt vmcnt(22)
	v_mfma_f32_16x16x32_bf16 v[22:25], v[108:111], v[104:107], v[22:25]
	s_waitcnt vmcnt(20)
	v_mfma_f32_16x16x32_bf16 v[22:25], v[116:119], v[112:115], v[22:25]
	s_waitcnt vmcnt(18)
	v_mfma_f32_16x16x32_bf16 v[22:25], v[124:127], v[120:123], v[22:25]
	s_waitcnt vmcnt(16)
	v_mfma_f32_16x16x32_bf16 v[22:25], v[132:135], v[128:131], v[22:25]
	s_waitcnt vmcnt(14)
	v_mfma_f32_16x16x32_bf16 v[22:25], v[166:169], v[162:165], v[22:25]
	s_waitcnt vmcnt(12)
	v_mfma_f32_16x16x32_bf16 v[22:25], v[174:177], v[170:173], v[22:25]
	s_waitcnt vmcnt(10)
	v_mfma_f32_16x16x32_bf16 v[22:25], v[182:185], v[178:181], v[22:25]
	s_waitcnt vmcnt(8)
	v_mfma_f32_16x16x32_bf16 v[22:25], v[190:193], v[186:189], v[22:25]
	s_waitcnt vmcnt(6)
	v_mfma_f32_16x16x32_bf16 v[22:25], v[198:201], v[194:197], v[22:25]
	s_waitcnt vmcnt(4)
	v_mfma_f32_16x16x32_bf16 v[22:25], v[206:209], v[202:205], v[22:25]
	s_waitcnt vmcnt(2)
	v_mfma_f32_16x16x32_bf16 v[22:25], v[214:217], v[210:213], v[22:25]
	s_waitcnt vmcnt(0)
	v_mfma_f32_16x16x32_bf16 v[22:25], v[236:239], v[218:221], v[22:25]
	v_mov_b32_e32 v28, v18
	v_mov_b32_e32 v29, v14
	v_mov_b32_e32 v14, v19
	v_mov_b32_e32 v18, v20
	v_mov_b32_e32 v19, v16
	v_mov_b32_e32 v16, v21
	v_pk_add_f32 v[14:15], v[28:29], v[14:15]
	v_pk_add_f32 v[16:17], v[18:19], v[16:17]
	v_readlane_b32 s8, v250, 43
	v_pk_add_f32 v[14:15], v[14:15], v[16:17]
	v_mov_b32_e32 v16, v10
	v_mov_b32_e32 v17, v6
	v_mov_b32_e32 v6, v11
	v_mov_b32_e32 v10, v12
	v_mov_b32_e32 v11, v8
	v_mov_b32_e32 v8, v13
	v_pk_add_f32 v[6:7], v[16:17], v[6:7]
	v_pk_add_f32 v[8:9], v[10:11], v[8:9]
	v_lshlrev_b64 v[10:11], 7, v[26:27]
	v_pk_add_f32 v[6:7], v[6:7], v[8:9]
	v_readlane_b32 s9, v250, 44
	v_pk_add_f32 v[6:7], v[14:15], v[6:7]
	v_and_b32_e32 v1, 3, v1
	v_add_f32_e32 v6, v6, v7
	v_fmamk_f32 v6, v6, 0x3a800000, v223
	v_rsq_f32_e32 v6, v6
	v_lshl_add_u64 v[10:11], s[8:9], 0, v[10:11]
	s_and_b32 s20, s6, 64
	v_readlane_b32 s6, v252, 45
	v_lshl_add_u64 v[10:11], v[10:11], 0, s[20:21]
	v_lshlrev_b32_e32 v138, 4, v1
	s_add_i32 s5, s5, s26
	s_add_i32 s4, s4, s6
	v_pk_mul_f32 v[8:9], v[6:7], v[24:25] op_sel_hi:[0,1]
	v_pk_mul_f32 v[6:7], v[6:7], v[22:23] op_sel_hi:[0,1]
	v_lshl_add_u64 v[10:11], v[10:11], 0, v[138:139]
	s_cmpk_gt_i32 s5, 0xff
	global_store_dwordx4 v[10:11], v[6:9], off
	s_cbranch_scc0 .LBB0_714
	s_mov_b64 s[50:51], s[10:11]
